# peel first K-iteration of all 9 GEMM K-loops with SrcC=0, remove per-tile accumulator zeroing
# speedup vs baseline: 1.0232x; 1.0118x over previous
.LBB0_191:
	s_ashr_i32 s39, s38, 31
	s_lshl_b64 s[40:41], s[38:39], 19
	s_add_u32 s40, s65, s40
	s_addc_u32 s41, s64, s41
	s_and_b64 s[42:43], s[4:5], exec
	s_cselect_b32 s39, s41, s47
	s_cselect_b32 s78, s40, s46
	s_ashr_i32 s37, s36, 31
	s_lshl_b64 s[42:43], s[36:37], 19
	s_add_u32 s42, s67, s42
	s_addc_u32 s43, s66, s43
	s_and_b64 s[80:81], s[4:5], exec
	s_cselect_b32 s37, s43, s49
	s_cselect_b32 s79, s42, s48
	s_add_u32 s46, s46, 0x40080
	s_addc_u32 s47, s47, 0
	s_add_u32 s80, s48, 0x100
	s_addc_u32 s81, s49, 0
	s_mov_b32 s82, -2
	s_add_u32 s48, s46, 0xfffc0080
	s_addc_u32 s49, s47, -1
	s_add_i32 s83, 0, 0x10000
	s_cmp_eq_u32 s82, 12
	s_cselect_b32 s49, s39, s49
	s_cselect_b32 s48, s78, s48
	v_add_u32_e32 v140, s83, v146
	s_cselect_b32 s85, s37, s81
	s_cselect_b32 s84, s79, s80
	s_add_i32 s86, 0, 0x14000
	ds_read_b128 v[136:139], v140
	ds_read_b128 v[152:155], v140 offset:1024
	ds_read_b128 v[156:159], v140 offset:2048
	ds_read_b128 v[160:163], v140 offset:3072
	v_add_u32_e32 v140, s86, v146
	ds_read_b128 v[164:167], v140
	ds_read_b128 v[168:171], v140 offset:1024
	ds_read_b128 v[172:175], v140 offset:2048
	ds_read_b128 v[176:179], v140 offset:3072
	v_lshl_add_u64 v[140:141], s[46:47], 0, v[132:133]
	s_add_i32 m0, s45, 0xc000
	ds_read_b128 v[180:183], v150
	ds_read_b128 v[184:187], v150 offset:1024
	ds_read_b128 v[188:191], v150 offset:2048
	ds_read_b128 v[192:195], v150 offset:3072
	ds_read_b128 v[196:199], v150 offset:4096
	ds_read_b128 v[200:203], v150 offset:5120
	ds_read_b128 v[204:207], v150 offset:6144
	ds_read_b128 v[208:211], v150 offset:7168
	global_load_lds_dwordx4 v[140:141], off
	v_lshl_add_u64 v[140:141], v[140:141], 0, s[12:13]
	s_add_i32 m0, s45, 0xe000
	s_nop 0
	global_load_lds_dwordx4 v[140:141], off
	s_waitcnt vmcnt(8)
	s_waitcnt lgkmcnt(0)
	s_barrier
	s_setprio 1
	s_waitcnt lgkmcnt(0)
	v_mfma_f32_16x16x32_bf16 v[124:127], v[136:139], v[180:183], 0
	v_mfma_f32_16x16x32_bf16 v[120:123], v[156:159], v[180:183], 0
	v_mfma_f32_16x16x32_bf16 v[112:115], v[136:139], v[188:191], 0
	v_mfma_f32_16x16x32_bf16 v[104:107], v[156:159], v[188:191], 0
	v_mfma_f32_16x16x32_bf16 v[96:99], v[136:139], v[196:199], 0
	v_mfma_f32_16x16x32_bf16 v[88:91], v[156:159], v[196:199], 0
	v_mfma_f32_16x16x32_bf16 v[80:83], v[136:139], v[204:207], 0
	v_mfma_f32_16x16x32_bf16 v[72:75], v[156:159], v[204:207], 0
	v_mfma_f32_16x16x32_bf16 v[124:127], v[152:155], v[184:187], v[124:127]
	v_mfma_f32_16x16x32_bf16 v[120:123], v[160:163], v[184:187], v[120:123]
	v_mfma_f32_16x16x32_bf16 v[112:115], v[152:155], v[192:195], v[112:115]
	v_mfma_f32_16x16x32_bf16 v[104:107], v[160:163], v[192:195], v[104:107]
	v_mfma_f32_16x16x32_bf16 v[96:99], v[152:155], v[200:203], v[96:99]
	v_mfma_f32_16x16x32_bf16 v[88:91], v[160:163], v[200:203], v[88:91]
	v_mfma_f32_16x16x32_bf16 v[80:83], v[152:155], v[208:211], v[80:83]
	v_mfma_f32_16x16x32_bf16 v[72:75], v[160:163], v[208:211], v[72:75]
	s_setprio 0
	s_setprio 1
	v_mfma_f32_16x16x32_bf16 v[116:119], v[164:167], v[180:183], 0
	v_mfma_f32_16x16x32_bf16 v[108:111], v[172:175], v[180:183], 0
	v_mfma_f32_16x16x32_bf16 v[100:103], v[164:167], v[188:191], 0
	v_mfma_f32_16x16x32_bf16 v[92:95], v[172:175], v[188:191], 0
	v_mfma_f32_16x16x32_bf16 v[84:87], v[164:167], v[196:199], 0
	v_mfma_f32_16x16x32_bf16 v[76:79], v[172:175], v[196:199], 0
	v_mfma_f32_16x16x32_bf16 v[68:71], v[164:167], v[204:207], 0
	v_mfma_f32_16x16x32_bf16 v[64:67], v[172:175], v[204:207], 0
	v_mfma_f32_16x16x32_bf16 v[116:119], v[168:171], v[184:187], v[116:119]
	v_mfma_f32_16x16x32_bf16 v[108:111], v[176:179], v[184:187], v[108:111]
	v_mfma_f32_16x16x32_bf16 v[100:103], v[168:171], v[192:195], v[100:103]
	v_mfma_f32_16x16x32_bf16 v[92:95], v[176:179], v[192:195], v[92:95]
	v_mfma_f32_16x16x32_bf16 v[84:87], v[168:171], v[200:203], v[84:87]
	v_mfma_f32_16x16x32_bf16 v[76:79], v[176:179], v[200:203], v[76:79]
	v_mfma_f32_16x16x32_bf16 v[68:71], v[168:171], v[208:211], v[68:71]
	v_mfma_f32_16x16x32_bf16 v[64:67], v[176:179], v[208:211], v[64:67]
	s_setprio 0
	s_barrier
	s_add_i32 s83, s83, s69
	v_lshl_add_u64 v[140:141], s[84:85], 0, v[128:129]
	s_mov_b32 m0, s83
	ds_read_b128 v[180:183], v150 offset:16384
	ds_read_b128 v[184:187], v150 offset:17408
	ds_read_b128 v[188:191], v150 offset:18432
	ds_read_b128 v[192:195], v150 offset:19456
	ds_read_b128 v[196:199], v150 offset:20480
	ds_read_b128 v[200:203], v150 offset:21504
	ds_read_b128 v[204:207], v150 offset:22528
	ds_read_b128 v[208:211], v150 offset:23552
	global_load_lds_dwordx4 v[140:141], off
	v_lshl_add_u64 v[212:213], v[140:141], 0, s[12:13]
	s_add_i32 m0, s83, 0x2000
	s_add_i32 s83, s86, s69
	global_load_lds_dwordx4 v[212:213], off
	v_lshl_add_u64 v[212:213], v[140:141], 0, s[14:15]
	s_mov_b32 m0, s83
	s_nop 0
	global_load_lds_dwordx4 v[212:213], off
	v_lshl_add_u64 v[212:213], v[140:141], 0, s[16:17]
	s_add_i32 m0, s83, 0x2000
	s_nop 0
	global_load_lds_dwordx4 v[212:213], off
	v_lshl_add_u64 v[212:213], s[48:49], 0, v[130:131]
	s_mov_b32 m0, s45
	v_lshl_add_u64 v[214:215], v[212:213], 0, s[12:13]
	global_load_lds_dwordx4 v[212:213], off
	s_mov_b32 m0, s71
	s_nop 0
	global_load_lds_dwordx4 v[214:215], off
	s_waitcnt vmcnt(8)
	s_waitcnt lgkmcnt(0)
	s_barrier
	s_setprio 1
	s_waitcnt lgkmcnt(0)
	v_mfma_f32_16x16x32_bf16 v[60:63], v[136:139], v[180:183], 0
	v_mfma_f32_16x16x32_bf16 v[56:59], v[156:159], v[180:183], 0
	v_mfma_f32_16x16x32_bf16 v[48:51], v[136:139], v[188:191], 0
	v_mfma_f32_16x16x32_bf16 v[40:43], v[156:159], v[188:191], 0
	v_mfma_f32_16x16x32_bf16 v[32:35], v[136:139], v[196:199], 0
	v_mfma_f32_16x16x32_bf16 v[24:27], v[156:159], v[196:199], 0
	v_mfma_f32_16x16x32_bf16 v[16:19], v[136:139], v[204:207], 0
	v_mfma_f32_16x16x32_bf16 v[8:11], v[156:159], v[204:207], 0
	v_mfma_f32_16x16x32_bf16 v[60:63], v[152:155], v[184:187], v[60:63]
	v_mfma_f32_16x16x32_bf16 v[56:59], v[160:163], v[184:187], v[56:59]
	v_mfma_f32_16x16x32_bf16 v[48:51], v[152:155], v[192:195], v[48:51]
	v_mfma_f32_16x16x32_bf16 v[40:43], v[160:163], v[192:195], v[40:43]
	v_mfma_f32_16x16x32_bf16 v[32:35], v[152:155], v[200:203], v[32:35]
	v_mfma_f32_16x16x32_bf16 v[24:27], v[160:163], v[200:203], v[24:27]
	v_mfma_f32_16x16x32_bf16 v[16:19], v[152:155], v[208:211], v[16:19]
	v_mfma_f32_16x16x32_bf16 v[8:11], v[160:163], v[208:211], v[8:11]
	s_setprio 0
	s_setprio 1
	v_mfma_f32_16x16x32_bf16 v[52:55], v[164:167], v[180:183], 0
	v_mfma_f32_16x16x32_bf16 v[44:47], v[172:175], v[180:183], 0
	v_mfma_f32_16x16x32_bf16 v[36:39], v[164:167], v[188:191], 0
	v_mfma_f32_16x16x32_bf16 v[28:31], v[172:175], v[188:191], 0
	v_mfma_f32_16x16x32_bf16 v[20:23], v[164:167], v[196:199], 0
	v_mfma_f32_16x16x32_bf16 v[12:15], v[172:175], v[196:199], 0
	v_mfma_f32_16x16x32_bf16 v[4:7], v[164:167], v[204:207], 0
	v_mfma_f32_16x16x32_bf16 v[0:3], v[172:175], v[204:207], 0
	v_mfma_f32_16x16x32_bf16 v[52:55], v[168:171], v[184:187], v[52:55]
	v_mfma_f32_16x16x32_bf16 v[44:47], v[176:179], v[184:187], v[44:47]
	v_mfma_f32_16x16x32_bf16 v[36:39], v[168:171], v[192:195], v[36:39]
	v_mfma_f32_16x16x32_bf16 v[28:31], v[176:179], v[192:195], v[28:31]
	v_mfma_f32_16x16x32_bf16 v[20:23], v[168:171], v[200:203], v[20:23]
	v_mfma_f32_16x16x32_bf16 v[12:15], v[176:179], v[200:203], v[12:15]
	v_mfma_f32_16x16x32_bf16 v[4:7], v[168:171], v[208:211], v[4:7]
	v_mfma_f32_16x16x32_bf16 v[0:3], v[176:179], v[208:211], v[0:3]
	s_setprio 0
	s_barrier
	s_add_i32 s48, 0, 0x18000
	v_add_u32_e32 v151, s48, v146
	s_add_i32 s49, 0, 0x1c000
	ds_read_b128 v[136:139], v151
	ds_read_b128 v[152:155], v151 offset:1024
	ds_read_b128 v[156:159], v151 offset:2048
	ds_read_b128 v[160:163], v151 offset:3072
	v_add_u32_e32 v151, s49, v146
	ds_read_b128 v[164:167], v151
	ds_read_b128 v[168:171], v151 offset:1024
	ds_read_b128 v[172:175], v151 offset:2048
	ds_read_b128 v[176:179], v151 offset:3072
	s_mov_b32 m0, s72
	v_lshl_add_u64 v[214:215], v[212:213], 0, s[14:15]
	ds_read_b128 v[180:183], v150 offset:32768
	ds_read_b128 v[184:187], v150 offset:33792
	ds_read_b128 v[188:191], v150 offset:34816
	ds_read_b128 v[192:195], v150 offset:35840
	ds_read_b128 v[196:199], v150 offset:36864
	ds_read_b128 v[200:203], v150 offset:37888
	ds_read_b128 v[204:207], v150 offset:38912
	ds_read_b128 v[208:211], v150 offset:39936
	global_load_lds_dwordx4 v[214:215], off
	v_lshl_add_u64 v[214:215], v[212:213], 0, s[16:17]
	s_mov_b32 m0, s73
	s_nop 0
	global_load_lds_dwordx4 v[214:215], off
	s_waitcnt vmcnt(8)
	s_waitcnt lgkmcnt(0)
	s_barrier
	s_setprio 1
	s_waitcnt lgkmcnt(0)
	v_mfma_f32_16x16x32_bf16 v[124:127], v[136:139], v[180:183], v[124:127]
	v_mfma_f32_16x16x32_bf16 v[120:123], v[156:159], v[180:183], v[120:123]
	v_mfma_f32_16x16x32_bf16 v[112:115], v[136:139], v[188:191], v[112:115]
	v_mfma_f32_16x16x32_bf16 v[104:107], v[156:159], v[188:191], v[104:107]
	v_mfma_f32_16x16x32_bf16 v[96:99], v[136:139], v[196:199], v[96:99]
	v_mfma_f32_16x16x32_bf16 v[88:91], v[156:159], v[196:199], v[88:91]
	v_mfma_f32_16x16x32_bf16 v[80:83], v[136:139], v[204:207], v[80:83]
	v_mfma_f32_16x16x32_bf16 v[72:75], v[156:159], v[204:207], v[72:75]
	v_mfma_f32_16x16x32_bf16 v[124:127], v[152:155], v[184:187], v[124:127]
	v_mfma_f32_16x16x32_bf16 v[120:123], v[160:163], v[184:187], v[120:123]
	v_mfma_f32_16x16x32_bf16 v[112:115], v[152:155], v[192:195], v[112:115]
	v_mfma_f32_16x16x32_bf16 v[104:107], v[160:163], v[192:195], v[104:107]
	v_mfma_f32_16x16x32_bf16 v[96:99], v[152:155], v[200:203], v[96:99]
	v_mfma_f32_16x16x32_bf16 v[88:91], v[160:163], v[200:203], v[88:91]
	v_mfma_f32_16x16x32_bf16 v[80:83], v[152:155], v[208:211], v[80:83]
	v_mfma_f32_16x16x32_bf16 v[72:75], v[160:163], v[208:211], v[72:75]
	s_setprio 0
	s_setprio 1
	v_mfma_f32_16x16x32_bf16 v[116:119], v[164:167], v[180:183], v[116:119]
	v_mfma_f32_16x16x32_bf16 v[108:111], v[172:175], v[180:183], v[108:111]
	v_mfma_f32_16x16x32_bf16 v[100:103], v[164:167], v[188:191], v[100:103]
	v_mfma_f32_16x16x32_bf16 v[92:95], v[172:175], v[188:191], v[92:95]
	v_mfma_f32_16x16x32_bf16 v[84:87], v[164:167], v[196:199], v[84:87]
	v_mfma_f32_16x16x32_bf16 v[76:79], v[172:175], v[196:199], v[76:79]
	v_mfma_f32_16x16x32_bf16 v[68:71], v[164:167], v[204:207], v[68:71]
	v_mfma_f32_16x16x32_bf16 v[64:67], v[172:175], v[204:207], v[64:67]
	v_mfma_f32_16x16x32_bf16 v[116:119], v[168:171], v[184:187], v[116:119]
	v_mfma_f32_16x16x32_bf16 v[108:111], v[176:179], v[184:187], v[108:111]
	v_mfma_f32_16x16x32_bf16 v[100:103], v[168:171], v[192:195], v[100:103]
	v_mfma_f32_16x16x32_bf16 v[92:95], v[176:179], v[192:195], v[92:95]
	v_mfma_f32_16x16x32_bf16 v[84:87], v[168:171], v[200:203], v[84:87]
	v_mfma_f32_16x16x32_bf16 v[76:79], v[176:179], v[200:203], v[76:79]
	v_mfma_f32_16x16x32_bf16 v[68:71], v[168:171], v[208:211], v[68:71]
	v_mfma_f32_16x16x32_bf16 v[64:67], v[176:179], v[208:211], v[64:67]
	s_setprio 0
	s_barrier
	s_add_i32 s48, s48, s69
	v_lshl_add_u64 v[214:215], v[140:141], 0, s[18:19]
	s_mov_b32 m0, s48
	ds_read_b128 v[180:183], v150 offset:49152
	ds_read_b128 v[184:187], v150 offset:50176
	ds_read_b128 v[188:191], v150 offset:51200
	ds_read_b128 v[192:195], v150 offset:52224
	ds_read_b128 v[196:199], v150 offset:53248
	ds_read_b128 v[200:203], v150 offset:54272
	ds_read_b128 v[204:207], v150 offset:55296
	ds_read_b128 v[208:211], v150 offset:56320
	global_load_lds_dwordx4 v[214:215], off
	v_lshl_add_u64 v[214:215], v[140:141], 0, s[20:21]
	s_add_i32 m0, s48, 0x2000
	s_add_i32 s48, s49, s69
	global_load_lds_dwordx4 v[214:215], off
	v_lshl_add_u64 v[214:215], v[140:141], 0, s[22:23]
	s_mov_b32 m0, s48
	v_lshl_add_u64 v[140:141], v[140:141], 0, s[24:25]
	global_load_lds_dwordx4 v[214:215], off
	s_add_i32 m0, s48, 0x2000
	s_nop 0
	global_load_lds_dwordx4 v[140:141], off
	v_lshl_add_u64 v[140:141], v[212:213], 0, s[18:19]
	s_mov_b32 m0, s10
	s_nop 0
	global_load_lds_dwordx4 v[140:141], off
	v_lshl_add_u64 v[140:141], v[212:213], 0, s[20:21]
	s_mov_b32 m0, s74
	s_nop 0
	global_load_lds_dwordx4 v[140:141], off
	s_waitcnt vmcnt(8)
	s_waitcnt lgkmcnt(0)
	s_barrier
	s_setprio 1
	s_waitcnt lgkmcnt(0)
	v_mfma_f32_16x16x32_bf16 v[60:63], v[136:139], v[180:183], v[60:63]
	v_mfma_f32_16x16x32_bf16 v[56:59], v[156:159], v[180:183], v[56:59]
	v_mfma_f32_16x16x32_bf16 v[48:51], v[136:139], v[188:191], v[48:51]
	v_mfma_f32_16x16x32_bf16 v[40:43], v[156:159], v[188:191], v[40:43]
	v_mfma_f32_16x16x32_bf16 v[32:35], v[136:139], v[196:199], v[32:35]
	v_mfma_f32_16x16x32_bf16 v[24:27], v[156:159], v[196:199], v[24:27]
	v_mfma_f32_16x16x32_bf16 v[16:19], v[136:139], v[204:207], v[16:19]
	v_mfma_f32_16x16x32_bf16 v[8:11], v[156:159], v[204:207], v[8:11]
	v_mfma_f32_16x16x32_bf16 v[60:63], v[152:155], v[184:187], v[60:63]
	v_mfma_f32_16x16x32_bf16 v[56:59], v[160:163], v[184:187], v[56:59]
	v_mfma_f32_16x16x32_bf16 v[48:51], v[152:155], v[192:195], v[48:51]
	v_mfma_f32_16x16x32_bf16 v[40:43], v[160:163], v[192:195], v[40:43]
	v_mfma_f32_16x16x32_bf16 v[32:35], v[152:155], v[200:203], v[32:35]
	v_mfma_f32_16x16x32_bf16 v[24:27], v[160:163], v[200:203], v[24:27]
	v_mfma_f32_16x16x32_bf16 v[16:19], v[152:155], v[208:211], v[16:19]
	v_mfma_f32_16x16x32_bf16 v[8:11], v[160:163], v[208:211], v[8:11]
	s_setprio 0
	s_setprio 1
	v_mfma_f32_16x16x32_bf16 v[52:55], v[164:167], v[180:183], v[52:55]
	v_mfma_f32_16x16x32_bf16 v[44:47], v[172:175], v[180:183], v[44:47]
	v_mfma_f32_16x16x32_bf16 v[36:39], v[164:167], v[188:191], v[36:39]
	v_mfma_f32_16x16x32_bf16 v[28:31], v[172:175], v[188:191], v[28:31]
	v_mfma_f32_16x16x32_bf16 v[20:23], v[164:167], v[196:199], v[20:23]
	v_mfma_f32_16x16x32_bf16 v[12:15], v[172:175], v[196:199], v[12:15]
	v_mfma_f32_16x16x32_bf16 v[4:7], v[164:167], v[204:207], v[4:7]
	v_mfma_f32_16x16x32_bf16 v[0:3], v[172:175], v[204:207], v[0:3]
	v_mfma_f32_16x16x32_bf16 v[52:55], v[168:171], v[184:187], v[52:55]
	v_mfma_f32_16x16x32_bf16 v[44:47], v[176:179], v[184:187], v[44:47]
	v_mfma_f32_16x16x32_bf16 v[36:39], v[168:171], v[192:195], v[36:39]
	v_mfma_f32_16x16x32_bf16 v[28:31], v[176:179], v[192:195], v[28:31]
	v_mfma_f32_16x16x32_bf16 v[20:23], v[168:171], v[200:203], v[20:23]
	v_mfma_f32_16x16x32_bf16 v[12:15], v[176:179], v[200:203], v[12:15]
	v_mfma_f32_16x16x32_bf16 v[4:7], v[168:171], v[208:211], v[4:7]
	v_mfma_f32_16x16x32_bf16 v[0:3], v[176:179], v[208:211], v[0:3]
	s_setprio 0
	s_barrier
	s_add_i32 s82, s82, 2
	s_add_u32 s46, s46, 0x100
	s_addc_u32 s47, s47, 0
	s_add_u32 s80, s80, 0x100
	s_addc_u32 s81, s81, 0
	s_cmp_gt_u32 s82, 13

.LBB0_228:
	s_ashr_i32 s45, s44, 31
	s_lshl_b64 s[46:47], s[44:45], 19
	s_add_u32 s46, s64, s46
	s_addc_u32 s47, s65, s47
	s_and_b64 s[48:49], s[38:39], exec
	s_cselect_b32 s22, s47, s15
	s_cselect_b32 s45, s46, s14
	s_ashr_i32 s43, s42, 31
	s_lshl_b64 s[48:49], s[42:43], 19
	s_add_u32 s48, s6, s48
	s_addc_u32 s49, s19, s49
	s_and_b64 s[60:61], s[38:39], exec
	s_cselect_b32 s43, s49, s17
	s_cselect_b32 s84, s48, s16
	s_add_u32 s60, s14, 0x40080
	s_addc_u32 s61, s15, 0
	s_add_u32 s16, s16, 0x100
	s_addc_u32 s17, s17, 0
	s_mov_b32 s85, -2
	s_add_u32 s14, s60, 0xfffc0080
	s_addc_u32 s15, s61, -1
	s_add_i32 s18, 0, 0x10000
	s_cmp_eq_u32 s85, 12
	s_cselect_b32 s15, s22, s15
	s_cselect_b32 s14, s45, s14
	v_add_u32_e32 v137, s18, v141
	s_cselect_b32 vcc_hi, s43, s17
	s_cselect_b32 vcc_lo, s84, s16
	s_add_i32 s21, 0, 0x14000
	ds_read_b128 v[146:149], v137
	ds_read_b128 v[150:153], v137 offset:1024
	ds_read_b128 v[154:157], v137 offset:2048
	ds_read_b128 v[158:161], v137 offset:3072
	v_add_u32_e32 v137, s21, v141
	ds_read_b128 v[162:165], v137
	ds_read_b128 v[166:169], v137 offset:1024
	ds_read_b128 v[170:173], v137 offset:2048
	ds_read_b128 v[174:177], v137 offset:3072
	v_lshl_add_u64 v[138:139], s[60:61], 0, v[184:185]
	s_add_i32 m0, s25, 0xc000
	ds_read_b128 v[178:181], v145
	ds_read_b128 v[194:197], v145 offset:1024
	ds_read_b128 v[198:201], v145 offset:2048
	ds_read_b128 v[202:205], v145 offset:3072
	ds_read_b128 v[206:209], v145 offset:4096
	ds_read_b128 v[210:213], v145 offset:5120
	ds_read_b128 v[214:217], v145 offset:6144
	ds_read_b128 v[218:221], v145 offset:7168
	global_load_lds_dwordx4 v[138:139], off
	v_lshl_add_u64 v[138:139], v[138:139], 0, s[34:35]
	s_add_i32 m0, s25, 0xe000
	s_nop 0
	global_load_lds_dwordx4 v[138:139], off
	s_waitcnt vmcnt(8)
	s_waitcnt lgkmcnt(0)
	s_barrier
	s_setprio 1
	s_waitcnt lgkmcnt(0)
	v_mfma_f32_16x16x32_bf16 v[124:127], v[146:149], v[178:181], 0
	v_mfma_f32_16x16x32_bf16 v[120:123], v[154:157], v[178:181], 0
	v_mfma_f32_16x16x32_bf16 v[112:115], v[146:149], v[198:201], 0
	v_mfma_f32_16x16x32_bf16 v[104:107], v[154:157], v[198:201], 0
	v_mfma_f32_16x16x32_bf16 v[96:99], v[146:149], v[206:209], 0
	v_mfma_f32_16x16x32_bf16 v[88:91], v[154:157], v[206:209], 0
	v_mfma_f32_16x16x32_bf16 v[80:83], v[146:149], v[214:217], 0
	v_mfma_f32_16x16x32_bf16 v[72:75], v[154:157], v[214:217], 0
	v_mfma_f32_16x16x32_bf16 v[124:127], v[150:153], v[194:197], v[124:127]
	v_mfma_f32_16x16x32_bf16 v[120:123], v[158:161], v[194:197], v[120:123]
	v_mfma_f32_16x16x32_bf16 v[112:115], v[150:153], v[202:205], v[112:115]
	v_mfma_f32_16x16x32_bf16 v[104:107], v[158:161], v[202:205], v[104:107]
	v_mfma_f32_16x16x32_bf16 v[96:99], v[150:153], v[210:213], v[96:99]
	v_mfma_f32_16x16x32_bf16 v[88:91], v[158:161], v[210:213], v[88:91]
	v_mfma_f32_16x16x32_bf16 v[80:83], v[150:153], v[218:221], v[80:83]
	v_mfma_f32_16x16x32_bf16 v[72:75], v[158:161], v[218:221], v[72:75]
	s_setprio 0
	s_setprio 1
	v_mfma_f32_16x16x32_bf16 v[116:119], v[162:165], v[178:181], 0
	v_mfma_f32_16x16x32_bf16 v[108:111], v[170:173], v[178:181], 0
	v_mfma_f32_16x16x32_bf16 v[100:103], v[162:165], v[198:201], 0
	v_mfma_f32_16x16x32_bf16 v[92:95], v[170:173], v[198:201], 0
	v_mfma_f32_16x16x32_bf16 v[84:87], v[162:165], v[206:209], 0
	v_mfma_f32_16x16x32_bf16 v[76:79], v[170:173], v[206:209], 0
	v_mfma_f32_16x16x32_bf16 v[68:71], v[162:165], v[214:217], 0
	v_mfma_f32_16x16x32_bf16 v[64:67], v[170:173], v[214:217], 0
	v_mfma_f32_16x16x32_bf16 v[116:119], v[166:169], v[194:197], v[116:119]
	v_mfma_f32_16x16x32_bf16 v[108:111], v[174:177], v[194:197], v[108:111]
	v_mfma_f32_16x16x32_bf16 v[100:103], v[166:169], v[202:205], v[100:103]
	v_mfma_f32_16x16x32_bf16 v[92:95], v[174:177], v[202:205], v[92:95]
	v_mfma_f32_16x16x32_bf16 v[84:87], v[166:169], v[210:213], v[84:87]
	v_mfma_f32_16x16x32_bf16 v[76:79], v[174:177], v[210:213], v[76:79]
	v_mfma_f32_16x16x32_bf16 v[68:71], v[166:169], v[218:221], v[68:71]
	v_mfma_f32_16x16x32_bf16 v[64:67], v[174:177], v[218:221], v[64:67]
	s_setprio 0
	s_barrier
	s_add_i32 s18, s18, s23
	v_lshl_add_u64 v[138:139], vcc, 0, v[128:129]
	s_mov_b32 m0, s18
	ds_read_b128 v[178:181], v145 offset:16384
	ds_read_b128 v[194:197], v145 offset:17408
	ds_read_b128 v[198:201], v145 offset:18432
	ds_read_b128 v[202:205], v145 offset:19456
	ds_read_b128 v[206:209], v145 offset:20480
	ds_read_b128 v[210:213], v145 offset:21504
	ds_read_b128 v[214:217], v145 offset:22528
	ds_read_b128 v[218:221], v145 offset:23552
	global_load_lds_dwordx4 v[138:139], off
	v_lshl_add_u64 v[182:183], v[138:139], 0, s[34:35]
	s_add_i32 m0, s18, 0x2000
	s_add_i32 s18, s21, s23
	global_load_lds_dwordx4 v[182:183], off
	v_lshl_add_u64 v[182:183], v[138:139], 0, s[92:93]
	s_mov_b32 m0, s18
	s_nop 0
	global_load_lds_dwordx4 v[182:183], off
	v_lshl_add_u64 v[182:183], v[138:139], 0, s[52:53]
	s_add_i32 m0, s18, 0x2000
	s_nop 0
	global_load_lds_dwordx4 v[182:183], off
	v_lshl_add_u64 v[182:183], s[14:15], 0, v[130:131]
	s_mov_b32 m0, s25
	v_lshl_add_u64 v[186:187], v[182:183], 0, s[34:35]
	global_load_lds_dwordx4 v[182:183], off
	s_mov_b32 m0, s26
	s_nop 0
	global_load_lds_dwordx4 v[186:187], off
	s_waitcnt vmcnt(8)
	s_waitcnt lgkmcnt(0)
	s_barrier
	s_setprio 1
	s_waitcnt lgkmcnt(0)
	v_mfma_f32_16x16x32_bf16 v[60:63], v[146:149], v[178:181], 0
	v_mfma_f32_16x16x32_bf16 v[56:59], v[154:157], v[178:181], 0
	v_mfma_f32_16x16x32_bf16 v[48:51], v[146:149], v[198:201], 0
	v_mfma_f32_16x16x32_bf16 v[40:43], v[154:157], v[198:201], 0
	v_mfma_f32_16x16x32_bf16 v[32:35], v[146:149], v[206:209], 0
	v_mfma_f32_16x16x32_bf16 v[24:27], v[154:157], v[206:209], 0
	v_mfma_f32_16x16x32_bf16 v[16:19], v[146:149], v[214:217], 0
	v_mfma_f32_16x16x32_bf16 v[8:11], v[154:157], v[214:217], 0
	v_mfma_f32_16x16x32_bf16 v[60:63], v[150:153], v[194:197], v[60:63]
	v_mfma_f32_16x16x32_bf16 v[56:59], v[158:161], v[194:197], v[56:59]
	v_mfma_f32_16x16x32_bf16 v[48:51], v[150:153], v[202:205], v[48:51]
	v_mfma_f32_16x16x32_bf16 v[40:43], v[158:161], v[202:205], v[40:43]
	v_mfma_f32_16x16x32_bf16 v[32:35], v[150:153], v[210:213], v[32:35]
	v_mfma_f32_16x16x32_bf16 v[24:27], v[158:161], v[210:213], v[24:27]
	v_mfma_f32_16x16x32_bf16 v[16:19], v[150:153], v[218:221], v[16:19]
	v_mfma_f32_16x16x32_bf16 v[8:11], v[158:161], v[218:221], v[8:11]
	s_setprio 0
	s_setprio 1
	v_mfma_f32_16x16x32_bf16 v[52:55], v[162:165], v[178:181], 0
	v_mfma_f32_16x16x32_bf16 v[44:47], v[170:173], v[178:181], 0
	v_mfma_f32_16x16x32_bf16 v[36:39], v[162:165], v[198:201], 0
	v_mfma_f32_16x16x32_bf16 v[28:31], v[170:173], v[198:201], 0
	v_mfma_f32_16x16x32_bf16 v[20:23], v[162:165], v[206:209], 0
	v_mfma_f32_16x16x32_bf16 v[12:15], v[170:173], v[206:209], 0
	v_mfma_f32_16x16x32_bf16 v[4:7], v[162:165], v[214:217], 0
	v_mfma_f32_16x16x32_bf16 v[0:3], v[170:173], v[214:217], 0
	v_mfma_f32_16x16x32_bf16 v[52:55], v[166:169], v[194:197], v[52:55]
	v_mfma_f32_16x16x32_bf16 v[44:47], v[174:177], v[194:197], v[44:47]
	v_mfma_f32_16x16x32_bf16 v[36:39], v[166:169], v[202:205], v[36:39]
	v_mfma_f32_16x16x32_bf16 v[28:31], v[174:177], v[202:205], v[28:31]
	v_mfma_f32_16x16x32_bf16 v[20:23], v[166:169], v[210:213], v[20:23]
	v_mfma_f32_16x16x32_bf16 v[12:15], v[174:177], v[210:213], v[12:15]
	v_mfma_f32_16x16x32_bf16 v[4:7], v[166:169], v[218:221], v[4:7]
	v_mfma_f32_16x16x32_bf16 v[0:3], v[174:177], v[218:221], v[0:3]
	s_setprio 0
	s_barrier
	s_add_i32 s14, 0, 0x18000
	v_add_u32_e32 v137, s14, v141
	s_add_i32 s15, 0, 0x1c000
	ds_read_b128 v[146:149], v137
	ds_read_b128 v[150:153], v137 offset:1024
	ds_read_b128 v[154:157], v137 offset:2048
	ds_read_b128 v[158:161], v137 offset:3072
	v_add_u32_e32 v137, s15, v141
	ds_read_b128 v[162:165], v137
	ds_read_b128 v[166:169], v137 offset:1024
	ds_read_b128 v[170:173], v137 offset:2048
	ds_read_b128 v[174:177], v137 offset:3072
	s_mov_b32 m0, s27
	v_lshl_add_u64 v[186:187], v[182:183], 0, s[92:93]
	ds_read_b128 v[178:181], v145 offset:32768
	ds_read_b128 v[194:197], v145 offset:33792
	ds_read_b128 v[198:201], v145 offset:34816
	ds_read_b128 v[202:205], v145 offset:35840
	ds_read_b128 v[206:209], v145 offset:36864
	ds_read_b128 v[210:213], v145 offset:37888
	ds_read_b128 v[214:217], v145 offset:38912
	ds_read_b128 v[218:221], v145 offset:39936
	global_load_lds_dwordx4 v[186:187], off
	v_lshl_add_u64 v[186:187], v[182:183], 0, s[52:53]
	s_mov_b32 m0, s28
	s_nop 0
	global_load_lds_dwordx4 v[186:187], off
	s_waitcnt vmcnt(8)
	s_waitcnt lgkmcnt(0)
	s_barrier
	s_setprio 1
	s_waitcnt lgkmcnt(0)
	v_mfma_f32_16x16x32_bf16 v[124:127], v[146:149], v[178:181], v[124:127]
	v_mfma_f32_16x16x32_bf16 v[120:123], v[154:157], v[178:181], v[120:123]
	v_mfma_f32_16x16x32_bf16 v[112:115], v[146:149], v[198:201], v[112:115]
	v_mfma_f32_16x16x32_bf16 v[104:107], v[154:157], v[198:201], v[104:107]
	v_mfma_f32_16x16x32_bf16 v[96:99], v[146:149], v[206:209], v[96:99]
	v_mfma_f32_16x16x32_bf16 v[88:91], v[154:157], v[206:209], v[88:91]
	v_mfma_f32_16x16x32_bf16 v[80:83], v[146:149], v[214:217], v[80:83]
	v_mfma_f32_16x16x32_bf16 v[72:75], v[154:157], v[214:217], v[72:75]
	v_mfma_f32_16x16x32_bf16 v[124:127], v[150:153], v[194:197], v[124:127]
	v_mfma_f32_16x16x32_bf16 v[120:123], v[158:161], v[194:197], v[120:123]
	v_mfma_f32_16x16x32_bf16 v[112:115], v[150:153], v[202:205], v[112:115]
	v_mfma_f32_16x16x32_bf16 v[104:107], v[158:161], v[202:205], v[104:107]
	v_mfma_f32_16x16x32_bf16 v[96:99], v[150:153], v[210:213], v[96:99]
	v_mfma_f32_16x16x32_bf16 v[88:91], v[158:161], v[210:213], v[88:91]
	v_mfma_f32_16x16x32_bf16 v[80:83], v[150:153], v[218:221], v[80:83]
	v_mfma_f32_16x16x32_bf16 v[72:75], v[158:161], v[218:221], v[72:75]
	s_setprio 0
	s_setprio 1
	v_mfma_f32_16x16x32_bf16 v[116:119], v[162:165], v[178:181], v[116:119]
	v_mfma_f32_16x16x32_bf16 v[108:111], v[170:173], v[178:181], v[108:111]
	v_mfma_f32_16x16x32_bf16 v[100:103], v[162:165], v[198:201], v[100:103]
	v_mfma_f32_16x16x32_bf16 v[92:95], v[170:173], v[198:201], v[92:95]
	v_mfma_f32_16x16x32_bf16 v[84:87], v[162:165], v[206:209], v[84:87]
	v_mfma_f32_16x16x32_bf16 v[76:79], v[170:173], v[206:209], v[76:79]
	v_mfma_f32_16x16x32_bf16 v[68:71], v[162:165], v[214:217], v[68:71]
	v_mfma_f32_16x16x32_bf16 v[64:67], v[170:173], v[214:217], v[64:67]
	v_mfma_f32_16x16x32_bf16 v[116:119], v[166:169], v[194:197], v[116:119]
	v_mfma_f32_16x16x32_bf16 v[108:111], v[174:177], v[194:197], v[108:111]
	v_mfma_f32_16x16x32_bf16 v[100:103], v[166:169], v[202:205], v[100:103]
	v_mfma_f32_16x16x32_bf16 v[92:95], v[174:177], v[202:205], v[92:95]
	v_mfma_f32_16x16x32_bf16 v[84:87], v[166:169], v[210:213], v[84:87]
	v_mfma_f32_16x16x32_bf16 v[76:79], v[174:177], v[210:213], v[76:79]
	v_mfma_f32_16x16x32_bf16 v[68:71], v[166:169], v[218:221], v[68:71]
	v_mfma_f32_16x16x32_bf16 v[64:67], v[174:177], v[218:221], v[64:67]
	s_setprio 0
	s_barrier
	s_add_i32 s14, s14, s23
	v_lshl_add_u64 v[186:187], v[138:139], 0, s[56:57]
	s_mov_b32 m0, s14
	ds_read_b128 v[178:181], v145 offset:49152
	ds_read_b128 v[194:197], v145 offset:50176
	ds_read_b128 v[198:201], v145 offset:51200
	ds_read_b128 v[202:205], v145 offset:52224
	ds_read_b128 v[206:209], v145 offset:53248
	ds_read_b128 v[210:213], v145 offset:54272
	ds_read_b128 v[214:217], v145 offset:55296
	ds_read_b128 v[218:221], v145 offset:56320
	global_load_lds_dwordx4 v[186:187], off
	v_lshl_add_u64 v[186:187], v[138:139], 0, s[96:97]
	s_add_i32 m0, s14, 0x2000
	s_add_i32 s14, s15, s23
	global_load_lds_dwordx4 v[186:187], off
	v_lshl_add_u64 v[186:187], v[138:139], 0, s[88:89]
	s_mov_b32 m0, s14
	v_lshl_add_u64 v[138:139], v[138:139], 0, s[68:69]
	global_load_lds_dwordx4 v[186:187], off
	s_add_i32 m0, s14, 0x2000
	s_nop 0
	global_load_lds_dwordx4 v[138:139], off
	v_lshl_add_u64 v[138:139], v[182:183], 0, s[56:57]
	s_mov_b32 m0, s29
	s_nop 0
	global_load_lds_dwordx4 v[138:139], off
	v_lshl_add_u64 v[138:139], v[182:183], 0, s[96:97]
	s_mov_b32 m0, s30
	s_nop 0
	global_load_lds_dwordx4 v[138:139], off
	s_waitcnt vmcnt(8)
	s_waitcnt lgkmcnt(0)
	s_barrier
	s_setprio 1
	s_waitcnt lgkmcnt(0)
	v_mfma_f32_16x16x32_bf16 v[60:63], v[146:149], v[178:181], v[60:63]
	v_mfma_f32_16x16x32_bf16 v[56:59], v[154:157], v[178:181], v[56:59]
	v_mfma_f32_16x16x32_bf16 v[48:51], v[146:149], v[198:201], v[48:51]
	v_mfma_f32_16x16x32_bf16 v[40:43], v[154:157], v[198:201], v[40:43]
	v_mfma_f32_16x16x32_bf16 v[32:35], v[146:149], v[206:209], v[32:35]
	v_mfma_f32_16x16x32_bf16 v[24:27], v[154:157], v[206:209], v[24:27]
	v_mfma_f32_16x16x32_bf16 v[16:19], v[146:149], v[214:217], v[16:19]
	v_mfma_f32_16x16x32_bf16 v[8:11], v[154:157], v[214:217], v[8:11]
	v_mfma_f32_16x16x32_bf16 v[60:63], v[150:153], v[194:197], v[60:63]
	v_mfma_f32_16x16x32_bf16 v[56:59], v[158:161], v[194:197], v[56:59]
	v_mfma_f32_16x16x32_bf16 v[48:51], v[150:153], v[202:205], v[48:51]
	v_mfma_f32_16x16x32_bf16 v[40:43], v[158:161], v[202:205], v[40:43]
	v_mfma_f32_16x16x32_bf16 v[32:35], v[150:153], v[210:213], v[32:35]
	v_mfma_f32_16x16x32_bf16 v[24:27], v[158:161], v[210:213], v[24:27]
	v_mfma_f32_16x16x32_bf16 v[16:19], v[150:153], v[218:221], v[16:19]
	v_mfma_f32_16x16x32_bf16 v[8:11], v[158:161], v[218:221], v[8:11]
	s_setprio 0
	s_setprio 1
	v_mfma_f32_16x16x32_bf16 v[52:55], v[162:165], v[178:181], v[52:55]
	v_mfma_f32_16x16x32_bf16 v[44:47], v[170:173], v[178:181], v[44:47]
	v_mfma_f32_16x16x32_bf16 v[36:39], v[162:165], v[198:201], v[36:39]
	v_mfma_f32_16x16x32_bf16 v[28:31], v[170:173], v[198:201], v[28:31]
	v_mfma_f32_16x16x32_bf16 v[20:23], v[162:165], v[206:209], v[20:23]
	v_mfma_f32_16x16x32_bf16 v[12:15], v[170:173], v[206:209], v[12:15]
	v_mfma_f32_16x16x32_bf16 v[4:7], v[162:165], v[214:217], v[4:7]
	v_mfma_f32_16x16x32_bf16 v[0:3], v[170:173], v[214:217], v[0:3]
	v_mfma_f32_16x16x32_bf16 v[52:55], v[166:169], v[194:197], v[52:55]
	v_mfma_f32_16x16x32_bf16 v[44:47], v[174:177], v[194:197], v[44:47]
	v_mfma_f32_16x16x32_bf16 v[36:39], v[166:169], v[202:205], v[36:39]
	v_mfma_f32_16x16x32_bf16 v[28:31], v[174:177], v[202:205], v[28:31]
	v_mfma_f32_16x16x32_bf16 v[20:23], v[166:169], v[210:213], v[20:23]
	v_mfma_f32_16x16x32_bf16 v[12:15], v[174:177], v[210:213], v[12:15]
	v_mfma_f32_16x16x32_bf16 v[4:7], v[166:169], v[218:221], v[4:7]
	v_mfma_f32_16x16x32_bf16 v[0:3], v[174:177], v[218:221], v[0:3]
	s_setprio 0
	s_barrier
	s_add_i32 s85, s85, 2
	s_add_u32 s60, s60, 0x100
	s_addc_u32 s61, s61, 0
	s_add_u32 s16, s16, 0x100
	s_addc_u32 s17, s17, 0
	s_cmp_gt_u32 s85, 13

.LBB0_248:
	s_ashr_i32 s45, s44, 31
	s_lshl_b64 s[46:47], s[44:45], 19
	s_add_u32 s46, s64, s46
	s_addc_u32 s47, s65, s47
	s_and_b64 s[48:49], s[38:39], exec
	s_cselect_b32 s22, s47, s15
	s_cselect_b32 s45, s46, s14
	s_ashr_i32 s43, s42, 31
	s_lshl_b64 s[48:49], s[42:43], 19
	s_add_u32 s48, s6, s48
	s_addc_u32 s49, s19, s49
	s_and_b64 s[60:61], s[38:39], exec
	s_cselect_b32 s43, s49, s17
	s_cselect_b32 s84, s48, s16
	s_add_u32 s60, s14, 0x40080
	s_addc_u32 s61, s15, 0
	s_add_u32 s16, s16, 0x100
	s_addc_u32 s17, s17, 0
	s_mov_b32 s85, -2
	s_add_u32 s14, s60, 0xfffc0080
	s_addc_u32 s15, s61, -1
	s_add_i32 s18, 0, 0x10000
	s_cmp_eq_u32 s85, 12
	s_cselect_b32 s15, s22, s15
	s_cselect_b32 s14, s45, s14
	s_waitcnt lgkmcnt(0)
	v_add_u32_e32 v137, s18, v149
	s_cselect_b32 vcc_hi, s43, s17
	s_cselect_b32 vcc_lo, s84, s16
	s_add_i32 s21, 0, 0x14000
	ds_read_b128 v[138:141], v137
	ds_read_b128 v[142:145], v137 offset:1024
	ds_read_b128 v[154:157], v137 offset:2048
	ds_read_b128 v[158:161], v137 offset:3072
	v_add_u32_e32 v137, s21, v149
	ds_read_b128 v[162:165], v137
	ds_read_b128 v[166:169], v137 offset:1024
	ds_read_b128 v[170:173], v137 offset:2048
	ds_read_b128 v[174:177], v137 offset:3072
	v_lshl_add_u64 v[146:147], s[60:61], 0, v[134:135]
	s_add_i32 m0, s25, 0xc000
	ds_read_b128 v[178:181], v153
	ds_read_b128 v[194:197], v153 offset:1024
	ds_read_b128 v[198:201], v153 offset:2048
	ds_read_b128 v[202:205], v153 offset:3072
	ds_read_b128 v[206:209], v153 offset:4096
	ds_read_b128 v[210:213], v153 offset:5120
	ds_read_b128 v[214:217], v153 offset:6144
	ds_read_b128 v[218:221], v153 offset:7168
	global_load_lds_dwordx4 v[146:147], off
	v_lshl_add_u64 v[146:147], v[146:147], 0, s[34:35]
	s_add_i32 m0, s25, 0xe000
	s_nop 0
	global_load_lds_dwordx4 v[146:147], off
	s_waitcnt vmcnt(8)
	s_waitcnt lgkmcnt(0)
	s_barrier
	s_setprio 1
	s_waitcnt lgkmcnt(0)
	v_mfma_f32_16x16x32_bf16 v[124:127], v[138:141], v[178:181], 0
	v_mfma_f32_16x16x32_bf16 v[120:123], v[154:157], v[178:181], 0
	v_mfma_f32_16x16x32_bf16 v[108:111], v[138:141], v[198:201], 0
	v_mfma_f32_16x16x32_bf16 v[104:107], v[154:157], v[198:201], 0
	v_mfma_f32_16x16x32_bf16 v[96:99], v[138:141], v[206:209], 0
	v_mfma_f32_16x16x32_bf16 v[88:91], v[154:157], v[206:209], 0
	v_mfma_f32_16x16x32_bf16 v[80:83], v[138:141], v[214:217], 0
	v_mfma_f32_16x16x32_bf16 v[72:75], v[154:157], v[214:217], 0
	v_mfma_f32_16x16x32_bf16 v[124:127], v[142:145], v[194:197], v[124:127]
	v_mfma_f32_16x16x32_bf16 v[120:123], v[158:161], v[194:197], v[120:123]
	v_mfma_f32_16x16x32_bf16 v[108:111], v[142:145], v[202:205], v[108:111]
	v_mfma_f32_16x16x32_bf16 v[104:107], v[158:161], v[202:205], v[104:107]
	v_mfma_f32_16x16x32_bf16 v[96:99], v[142:145], v[210:213], v[96:99]
	v_mfma_f32_16x16x32_bf16 v[88:91], v[158:161], v[210:213], v[88:91]
	v_mfma_f32_16x16x32_bf16 v[80:83], v[142:145], v[218:221], v[80:83]
	v_mfma_f32_16x16x32_bf16 v[72:75], v[158:161], v[218:221], v[72:75]
	s_setprio 0
	s_setprio 1
	v_mfma_f32_16x16x32_bf16 v[116:119], v[162:165], v[178:181], 0
	v_mfma_f32_16x16x32_bf16 v[112:115], v[170:173], v[178:181], 0
	v_mfma_f32_16x16x32_bf16 v[100:103], v[162:165], v[198:201], 0
	v_mfma_f32_16x16x32_bf16 v[92:95], v[170:173], v[198:201], 0
	v_mfma_f32_16x16x32_bf16 v[84:87], v[162:165], v[206:209], 0
	v_mfma_f32_16x16x32_bf16 v[76:79], v[170:173], v[206:209], 0
	v_mfma_f32_16x16x32_bf16 v[68:71], v[162:165], v[214:217], 0
	v_mfma_f32_16x16x32_bf16 v[64:67], v[170:173], v[214:217], 0
	v_mfma_f32_16x16x32_bf16 v[116:119], v[166:169], v[194:197], v[116:119]
	v_mfma_f32_16x16x32_bf16 v[112:115], v[174:177], v[194:197], v[112:115]
	v_mfma_f32_16x16x32_bf16 v[100:103], v[166:169], v[202:205], v[100:103]
	v_mfma_f32_16x16x32_bf16 v[92:95], v[174:177], v[202:205], v[92:95]
	v_mfma_f32_16x16x32_bf16 v[84:87], v[166:169], v[210:213], v[84:87]
	v_mfma_f32_16x16x32_bf16 v[76:79], v[174:177], v[210:213], v[76:79]
	v_mfma_f32_16x16x32_bf16 v[68:71], v[166:169], v[218:221], v[68:71]
	v_mfma_f32_16x16x32_bf16 v[64:67], v[174:177], v[218:221], v[64:67]
	s_setprio 0
	s_barrier
	s_add_i32 s18, s18, s23
	v_lshl_add_u64 v[146:147], vcc, 0, v[128:129]
	s_mov_b32 m0, s18
	ds_read_b128 v[178:181], v153 offset:16384
	ds_read_b128 v[194:197], v153 offset:17408
	ds_read_b128 v[198:201], v153 offset:18432
	ds_read_b128 v[202:205], v153 offset:19456
	ds_read_b128 v[206:209], v153 offset:20480
	ds_read_b128 v[210:213], v153 offset:21504
	ds_read_b128 v[214:217], v153 offset:22528
	ds_read_b128 v[218:221], v153 offset:23552
	global_load_lds_dwordx4 v[146:147], off
	v_lshl_add_u64 v[182:183], v[146:147], 0, s[34:35]
	s_add_i32 m0, s18, 0x2000
	s_add_i32 s18, s21, s23
	global_load_lds_dwordx4 v[182:183], off
	v_lshl_add_u64 v[182:183], v[146:147], 0, s[92:93]
	s_mov_b32 m0, s18
	s_nop 0
	global_load_lds_dwordx4 v[182:183], off
	v_lshl_add_u64 v[182:183], v[146:147], 0, s[52:53]
	s_add_i32 m0, s18, 0x2000
	s_nop 0
	global_load_lds_dwordx4 v[182:183], off
	v_lshl_add_u64 v[182:183], s[14:15], 0, v[130:131]
	s_mov_b32 m0, s25
	v_lshl_add_u64 v[186:187], v[182:183], 0, s[34:35]
	global_load_lds_dwordx4 v[182:183], off
	s_mov_b32 m0, s26
	s_nop 0
	global_load_lds_dwordx4 v[186:187], off
	s_waitcnt vmcnt(8)
	s_waitcnt lgkmcnt(0)
	s_barrier
	s_setprio 1
	s_waitcnt lgkmcnt(0)
	v_mfma_f32_16x16x32_bf16 v[60:63], v[138:141], v[178:181], 0
	v_mfma_f32_16x16x32_bf16 v[56:59], v[154:157], v[178:181], 0
	v_mfma_f32_16x16x32_bf16 v[48:51], v[138:141], v[198:201], 0
	v_mfma_f32_16x16x32_bf16 v[40:43], v[154:157], v[198:201], 0
	v_mfma_f32_16x16x32_bf16 v[32:35], v[138:141], v[206:209], 0
	v_mfma_f32_16x16x32_bf16 v[24:27], v[154:157], v[206:209], 0
	v_mfma_f32_16x16x32_bf16 v[16:19], v[138:141], v[214:217], 0
	v_mfma_f32_16x16x32_bf16 v[8:11], v[154:157], v[214:217], 0
	v_mfma_f32_16x16x32_bf16 v[60:63], v[142:145], v[194:197], v[60:63]
	v_mfma_f32_16x16x32_bf16 v[56:59], v[158:161], v[194:197], v[56:59]
	v_mfma_f32_16x16x32_bf16 v[48:51], v[142:145], v[202:205], v[48:51]
	v_mfma_f32_16x16x32_bf16 v[40:43], v[158:161], v[202:205], v[40:43]
	v_mfma_f32_16x16x32_bf16 v[32:35], v[142:145], v[210:213], v[32:35]
	v_mfma_f32_16x16x32_bf16 v[24:27], v[158:161], v[210:213], v[24:27]
	v_mfma_f32_16x16x32_bf16 v[16:19], v[142:145], v[218:221], v[16:19]
	v_mfma_f32_16x16x32_bf16 v[8:11], v[158:161], v[218:221], v[8:11]
	s_setprio 0
	s_setprio 1
	v_mfma_f32_16x16x32_bf16 v[52:55], v[162:165], v[178:181], 0
	v_mfma_f32_16x16x32_bf16 v[44:47], v[170:173], v[178:181], 0
	v_mfma_f32_16x16x32_bf16 v[36:39], v[162:165], v[198:201], 0
	v_mfma_f32_16x16x32_bf16 v[28:31], v[170:173], v[198:201], 0
	v_mfma_f32_16x16x32_bf16 v[20:23], v[162:165], v[206:209], 0
	v_mfma_f32_16x16x32_bf16 v[12:15], v[170:173], v[206:209], 0
	v_mfma_f32_16x16x32_bf16 v[4:7], v[162:165], v[214:217], 0
	v_mfma_f32_16x16x32_bf16 v[0:3], v[170:173], v[214:217], 0
	v_mfma_f32_16x16x32_bf16 v[52:55], v[166:169], v[194:197], v[52:55]
	v_mfma_f32_16x16x32_bf16 v[44:47], v[174:177], v[194:197], v[44:47]
	v_mfma_f32_16x16x32_bf16 v[36:39], v[166:169], v[202:205], v[36:39]
	v_mfma_f32_16x16x32_bf16 v[28:31], v[174:177], v[202:205], v[28:31]
	v_mfma_f32_16x16x32_bf16 v[20:23], v[166:169], v[210:213], v[20:23]
	v_mfma_f32_16x16x32_bf16 v[12:15], v[174:177], v[210:213], v[12:15]
	v_mfma_f32_16x16x32_bf16 v[4:7], v[166:169], v[218:221], v[4:7]
	v_mfma_f32_16x16x32_bf16 v[0:3], v[174:177], v[218:221], v[0:3]
	s_setprio 0
	s_barrier
	s_add_i32 s14, 0, 0x18000
	v_add_u32_e32 v137, s14, v149
	s_add_i32 s15, 0, 0x1c000
	ds_read_b128 v[138:141], v137
	ds_read_b128 v[142:145], v137 offset:1024
	ds_read_b128 v[154:157], v137 offset:2048
	ds_read_b128 v[158:161], v137 offset:3072
	v_add_u32_e32 v137, s15, v149
	ds_read_b128 v[162:165], v137
	ds_read_b128 v[166:169], v137 offset:1024
	ds_read_b128 v[170:173], v137 offset:2048
	ds_read_b128 v[174:177], v137 offset:3072
	s_mov_b32 m0, s27
	v_lshl_add_u64 v[186:187], v[182:183], 0, s[92:93]
	ds_read_b128 v[178:181], v153 offset:32768
	ds_read_b128 v[194:197], v153 offset:33792
	ds_read_b128 v[198:201], v153 offset:34816
	ds_read_b128 v[202:205], v153 offset:35840
	ds_read_b128 v[206:209], v153 offset:36864
	ds_read_b128 v[210:213], v153 offset:37888
	ds_read_b128 v[214:217], v153 offset:38912
	ds_read_b128 v[218:221], v153 offset:39936
	global_load_lds_dwordx4 v[186:187], off
	v_lshl_add_u64 v[186:187], v[182:183], 0, s[52:53]
	s_mov_b32 m0, s28
	s_nop 0
	global_load_lds_dwordx4 v[186:187], off
	s_waitcnt vmcnt(8)
	s_waitcnt lgkmcnt(0)
	s_barrier
	s_setprio 1
	s_waitcnt lgkmcnt(0)
	v_mfma_f32_16x16x32_bf16 v[124:127], v[138:141], v[178:181], v[124:127]
	v_mfma_f32_16x16x32_bf16 v[120:123], v[154:157], v[178:181], v[120:123]
	v_mfma_f32_16x16x32_bf16 v[108:111], v[138:141], v[198:201], v[108:111]
	v_mfma_f32_16x16x32_bf16 v[104:107], v[154:157], v[198:201], v[104:107]
	v_mfma_f32_16x16x32_bf16 v[96:99], v[138:141], v[206:209], v[96:99]
	v_mfma_f32_16x16x32_bf16 v[88:91], v[154:157], v[206:209], v[88:91]
	v_mfma_f32_16x16x32_bf16 v[80:83], v[138:141], v[214:217], v[80:83]
	v_mfma_f32_16x16x32_bf16 v[72:75], v[154:157], v[214:217], v[72:75]
	v_mfma_f32_16x16x32_bf16 v[124:127], v[142:145], v[194:197], v[124:127]
	v_mfma_f32_16x16x32_bf16 v[120:123], v[158:161], v[194:197], v[120:123]
	v_mfma_f32_16x16x32_bf16 v[108:111], v[142:145], v[202:205], v[108:111]
	v_mfma_f32_16x16x32_bf16 v[104:107], v[158:161], v[202:205], v[104:107]
	v_mfma_f32_16x16x32_bf16 v[96:99], v[142:145], v[210:213], v[96:99]
	v_mfma_f32_16x16x32_bf16 v[88:91], v[158:161], v[210:213], v[88:91]
	v_mfma_f32_16x16x32_bf16 v[80:83], v[142:145], v[218:221], v[80:83]
	v_mfma_f32_16x16x32_bf16 v[72:75], v[158:161], v[218:221], v[72:75]
	s_setprio 0
	s_setprio 1
	v_mfma_f32_16x16x32_bf16 v[116:119], v[162:165], v[178:181], v[116:119]
	v_mfma_f32_16x16x32_bf16 v[112:115], v[170:173], v[178:181], v[112:115]
	v_mfma_f32_16x16x32_bf16 v[100:103], v[162:165], v[198:201], v[100:103]
	v_mfma_f32_16x16x32_bf16 v[92:95], v[170:173], v[198:201], v[92:95]
	v_mfma_f32_16x16x32_bf16 v[84:87], v[162:165], v[206:209], v[84:87]
	v_mfma_f32_16x16x32_bf16 v[76:79], v[170:173], v[206:209], v[76:79]
	v_mfma_f32_16x16x32_bf16 v[68:71], v[162:165], v[214:217], v[68:71]
	v_mfma_f32_16x16x32_bf16 v[64:67], v[170:173], v[214:217], v[64:67]
	v_mfma_f32_16x16x32_bf16 v[116:119], v[166:169], v[194:197], v[116:119]
	v_mfma_f32_16x16x32_bf16 v[112:115], v[174:177], v[194:197], v[112:115]
	v_mfma_f32_16x16x32_bf16 v[100:103], v[166:169], v[202:205], v[100:103]
	v_mfma_f32_16x16x32_bf16 v[92:95], v[174:177], v[202:205], v[92:95]
	v_mfma_f32_16x16x32_bf16 v[84:87], v[166:169], v[210:213], v[84:87]
	v_mfma_f32_16x16x32_bf16 v[76:79], v[174:177], v[210:213], v[76:79]
	v_mfma_f32_16x16x32_bf16 v[68:71], v[166:169], v[218:221], v[68:71]
	v_mfma_f32_16x16x32_bf16 v[64:67], v[174:177], v[218:221], v[64:67]
	s_setprio 0
	s_barrier
	s_add_i32 s14, s14, s23
	v_lshl_add_u64 v[186:187], v[146:147], 0, s[56:57]
	s_mov_b32 m0, s14
	ds_read_b128 v[178:181], v153 offset:49152
	ds_read_b128 v[194:197], v153 offset:50176
	ds_read_b128 v[198:201], v153 offset:51200
	ds_read_b128 v[202:205], v153 offset:52224
	ds_read_b128 v[206:209], v153 offset:53248
	ds_read_b128 v[210:213], v153 offset:54272
	ds_read_b128 v[214:217], v153 offset:55296
	ds_read_b128 v[218:221], v153 offset:56320
	global_load_lds_dwordx4 v[186:187], off
	v_lshl_add_u64 v[186:187], v[146:147], 0, s[96:97]
	s_add_i32 m0, s14, 0x2000
	s_add_i32 s14, s15, s23
	global_load_lds_dwordx4 v[186:187], off
	v_lshl_add_u64 v[186:187], v[146:147], 0, s[88:89]
	s_mov_b32 m0, s14
	v_lshl_add_u64 v[146:147], v[146:147], 0, s[68:69]
	global_load_lds_dwordx4 v[186:187], off
	s_add_i32 m0, s14, 0x2000
	s_nop 0
	global_load_lds_dwordx4 v[146:147], off
	v_lshl_add_u64 v[146:147], v[182:183], 0, s[56:57]
	s_mov_b32 m0, s29
	s_nop 0
	global_load_lds_dwordx4 v[146:147], off
	v_lshl_add_u64 v[146:147], v[182:183], 0, s[96:97]
	s_mov_b32 m0, s30
	s_nop 0
	global_load_lds_dwordx4 v[146:147], off
	s_waitcnt vmcnt(8)
	s_waitcnt lgkmcnt(0)
	s_barrier
	s_setprio 1
	s_waitcnt lgkmcnt(0)
	v_mfma_f32_16x16x32_bf16 v[60:63], v[138:141], v[178:181], v[60:63]
	v_mfma_f32_16x16x32_bf16 v[56:59], v[154:157], v[178:181], v[56:59]
	v_mfma_f32_16x16x32_bf16 v[48:51], v[138:141], v[198:201], v[48:51]
	v_mfma_f32_16x16x32_bf16 v[40:43], v[154:157], v[198:201], v[40:43]
	v_mfma_f32_16x16x32_bf16 v[32:35], v[138:141], v[206:209], v[32:35]
	v_mfma_f32_16x16x32_bf16 v[24:27], v[154:157], v[206:209], v[24:27]
	v_mfma_f32_16x16x32_bf16 v[16:19], v[138:141], v[214:217], v[16:19]
	v_mfma_f32_16x16x32_bf16 v[8:11], v[154:157], v[214:217], v[8:11]
	v_mfma_f32_16x16x32_bf16 v[60:63], v[142:145], v[194:197], v[60:63]
	v_mfma_f32_16x16x32_bf16 v[56:59], v[158:161], v[194:197], v[56:59]
	v_mfma_f32_16x16x32_bf16 v[48:51], v[142:145], v[202:205], v[48:51]
	v_mfma_f32_16x16x32_bf16 v[40:43], v[158:161], v[202:205], v[40:43]
	v_mfma_f32_16x16x32_bf16 v[32:35], v[142:145], v[210:213], v[32:35]
	v_mfma_f32_16x16x32_bf16 v[24:27], v[158:161], v[210:213], v[24:27]
	v_mfma_f32_16x16x32_bf16 v[16:19], v[142:145], v[218:221], v[16:19]
	v_mfma_f32_16x16x32_bf16 v[8:11], v[158:161], v[218:221], v[8:11]
	s_setprio 0
	s_setprio 1
	v_mfma_f32_16x16x32_bf16 v[52:55], v[162:165], v[178:181], v[52:55]
	v_mfma_f32_16x16x32_bf16 v[44:47], v[170:173], v[178:181], v[44:47]
	v_mfma_f32_16x16x32_bf16 v[36:39], v[162:165], v[198:201], v[36:39]
	v_mfma_f32_16x16x32_bf16 v[28:31], v[170:173], v[198:201], v[28:31]
	v_mfma_f32_16x16x32_bf16 v[20:23], v[162:165], v[206:209], v[20:23]
	v_mfma_f32_16x16x32_bf16 v[12:15], v[170:173], v[206:209], v[12:15]
	v_mfma_f32_16x16x32_bf16 v[4:7], v[162:165], v[214:217], v[4:7]
	v_mfma_f32_16x16x32_bf16 v[0:3], v[170:173], v[214:217], v[0:3]
	v_mfma_f32_16x16x32_bf16 v[52:55], v[166:169], v[194:197], v[52:55]
	v_mfma_f32_16x16x32_bf16 v[44:47], v[174:177], v[194:197], v[44:47]
	v_mfma_f32_16x16x32_bf16 v[36:39], v[166:169], v[202:205], v[36:39]
	v_mfma_f32_16x16x32_bf16 v[28:31], v[174:177], v[202:205], v[28:31]
	v_mfma_f32_16x16x32_bf16 v[20:23], v[166:169], v[210:213], v[20:23]
	v_mfma_f32_16x16x32_bf16 v[12:15], v[174:177], v[210:213], v[12:15]
	v_mfma_f32_16x16x32_bf16 v[4:7], v[166:169], v[218:221], v[4:7]
	v_mfma_f32_16x16x32_bf16 v[0:3], v[174:177], v[218:221], v[0:3]
	s_setprio 0
	s_barrier
	s_add_i32 s85, s85, 2
	s_add_u32 s60, s60, 0x100
	s_addc_u32 s61, s61, 0
	s_add_u32 s16, s16, 0x100
	s_addc_u32 s17, s17, 0
	s_cmp_gt_u32 s85, 13

.LBB0_316:
	s_add_u32 s50, s16, 0x58080
	s_addc_u32 s51, s17, 0
	s_add_u32 s70, s14, 0x100
	s_addc_u32 s84, s15, 0
	s_mov_b32 s85, -2
	s_waitcnt lgkmcnt(0)
	s_mov_b64 vcc, 0x2c000
	s_mov_b64 s[82:83], 0x84000
	s_mov_b64 s[80:81], 0x2c080
	s_mov_b64 s[74:75], 0x58080
	s_mov_b64 s[62:63], 0x84080
	s_add_u32 s14, s50, 0xfffa8080
	s_addc_u32 s15, s51, -1
	s_add_i32 s22, 0, 0x10000
	s_cmp_eq_u32 s85, 18
	s_cselect_b32 s15, s1, s15
	s_cselect_b32 s14, s0, s14
	s_cselect_b32 s17, s49, s84
	s_cselect_b32 s16, s48, s70
	s_add_i32 s23, 0, 0x14000
	v_add_u32_e32 v0, s22, v221
	v_add_u32_e32 v4, s23, v221
	ds_read_b128 v[24:27], v0
	ds_read_b128 v[28:31], v0 offset:1024
	ds_read_b128 v[16:19], v0 offset:2048
	ds_read_b128 v[20:23], v0 offset:3072
	ds_read_b128 v[8:11], v4
	ds_read_b128 v[12:15], v4 offset:1024
	ds_read_b128 v[0:3], v4 offset:2048
	ds_read_b128 v[4:7], v4 offset:3072
	v_lshl_add_u64 v[206:207], s[50:51], 0, v[196:197]
	s_add_i32 m0, s19, 0xc000
	ds_read_b128 v[160:163], v223
	ds_read_b128 v[164:167], v223 offset:1024
	ds_read_b128 v[168:171], v223 offset:2048
	ds_read_b128 v[172:175], v223 offset:3072
	ds_read_b128 v[176:179], v223 offset:4096
	ds_read_b128 v[180:183], v223 offset:5120
	ds_read_b128 v[198:201], v223 offset:6144
	ds_read_b128 v[202:205], v223 offset:7168
	global_load_lds_dwordx4 v[206:207], off
	v_lshl_add_u64 v[206:207], v[206:207], 0, vcc
	s_add_i32 m0, s19, 0xe000
	s_nop 0
	global_load_lds_dwordx4 v[206:207], off
	s_waitcnt vmcnt(8)
	s_waitcnt lgkmcnt(0)
	s_barrier
	s_setprio 1
	s_waitcnt lgkmcnt(0)
	v_mfma_scale_f32_16x16x128_f8f6f4 v[156:159], v[24:31], v[160:167], 0, v240, v240 op_sel_hi:[0,0,0]
	v_mfma_scale_f32_16x16x128_f8f6f4 v[152:155], v[16:23], v[160:167], 0, v240, v240 op_sel_hi:[0,0,0]
	v_mfma_scale_f32_16x16x128_f8f6f4 v[140:143], v[24:31], v[168:175], 0, v240, v240 op_sel_hi:[0,0,0]
	v_mfma_scale_f32_16x16x128_f8f6f4 v[136:139], v[16:23], v[168:175], 0, v240, v240 op_sel_hi:[0,0,0]
	v_mfma_scale_f32_16x16x128_f8f6f4 v[124:127], v[24:31], v[176:183], 0, v240, v240 op_sel_hi:[0,0,0]
	v_mfma_scale_f32_16x16x128_f8f6f4 v[120:123], v[16:23], v[176:183], 0, v240, v240 op_sel_hi:[0,0,0]
	v_mfma_scale_f32_16x16x128_f8f6f4 v[108:111], v[24:31], v[198:205], 0, v240, v240 op_sel_hi:[0,0,0]
	v_mfma_scale_f32_16x16x128_f8f6f4 v[104:107], v[16:23], v[198:205], 0, v240, v240 op_sel_hi:[0,0,0]
	s_setprio 0
	s_setprio 1
	v_mfma_scale_f32_16x16x128_f8f6f4 v[148:151], v[8:15], v[160:167], 0, v240, v240 op_sel_hi:[0,0,0]
	v_mfma_scale_f32_16x16x128_f8f6f4 v[144:147], v[0:7], v[160:167], 0, v240, v240 op_sel_hi:[0,0,0]
	v_mfma_scale_f32_16x16x128_f8f6f4 v[132:135], v[8:15], v[168:175], 0, v240, v240 op_sel_hi:[0,0,0]
	v_mfma_scale_f32_16x16x128_f8f6f4 v[128:131], v[0:7], v[168:175], 0, v240, v240 op_sel_hi:[0,0,0]
	v_mfma_scale_f32_16x16x128_f8f6f4 v[116:119], v[8:15], v[176:183], 0, v240, v240 op_sel_hi:[0,0,0]
	v_mfma_scale_f32_16x16x128_f8f6f4 v[112:115], v[0:7], v[176:183], 0, v240, v240 op_sel_hi:[0,0,0]
	v_mfma_scale_f32_16x16x128_f8f6f4 v[100:103], v[8:15], v[198:205], 0, v240, v240 op_sel_hi:[0,0,0]
	v_mfma_scale_f32_16x16x128_f8f6f4 v[96:99], v[0:7], v[198:205], 0, v240, v240 op_sel_hi:[0,0,0]
	s_setprio 0
	s_barrier
	v_lshl_add_u64 v[160:161], s[16:17], 0, v[184:185]
	s_add_i32 s16, s22, s6
	s_mov_b32 m0, s16
	ds_read_b128 v[164:167], v223 offset:16384
	ds_read_b128 v[168:171], v223 offset:17408
	ds_read_b128 v[172:175], v223 offset:18432
	ds_read_b128 v[176:179], v223 offset:19456
	ds_read_b128 v[198:201], v223 offset:20480
	ds_read_b128 v[202:205], v223 offset:21504
	ds_read_b128 v[206:209], v223 offset:22528
	ds_read_b128 v[210:213], v223 offset:23552
	global_load_lds_dwordx4 v[160:161], off
	v_lshl_add_u64 v[162:163], v[160:161], 0, vcc
	s_add_i32 m0, s16, 0x2000
	s_add_i32 s16, s23, s6
	global_load_lds_dwordx4 v[162:163], off
	v_lshl_add_u64 v[162:163], v[160:161], 0, s[2:3]
	s_mov_b32 m0, s16
	s_nop 0
	global_load_lds_dwordx4 v[162:163], off
	v_lshl_add_u64 v[162:163], v[160:161], 0, s[82:83]
	s_add_i32 m0, s16, 0x2000
	s_nop 0
	global_load_lds_dwordx4 v[162:163], off
	v_lshl_add_u64 v[162:163], s[14:15], 0, v[194:195]
	s_mov_b32 m0, s19
	v_lshl_add_u64 v[180:181], v[162:163], 0, vcc
	global_load_lds_dwordx4 v[162:163], off
	s_mov_b32 m0, s20
	s_nop 0
	global_load_lds_dwordx4 v[180:181], off
	s_waitcnt vmcnt(8)
	s_waitcnt lgkmcnt(0)
	s_barrier
	s_setprio 1
	s_waitcnt lgkmcnt(0)
	v_mfma_scale_f32_16x16x128_f8f6f4 v[92:95], v[24:31], v[164:171], 0, v240, v240 op_sel_hi:[0,0,0]
	v_mfma_scale_f32_16x16x128_f8f6f4 v[88:91], v[16:23], v[164:171], 0, v240, v240 op_sel_hi:[0,0,0]
	v_mfma_scale_f32_16x16x128_f8f6f4 v[76:79], v[24:31], v[172:179], 0, v240, v240 op_sel_hi:[0,0,0]
	v_mfma_scale_f32_16x16x128_f8f6f4 v[72:75], v[16:23], v[172:179], 0, v240, v240 op_sel_hi:[0,0,0]
	v_mfma_scale_f32_16x16x128_f8f6f4 v[60:63], v[24:31], v[198:205], 0, v240, v240 op_sel_hi:[0,0,0]
	v_mfma_scale_f32_16x16x128_f8f6f4 v[56:59], v[16:23], v[198:205], 0, v240, v240 op_sel_hi:[0,0,0]
	v_mfma_scale_f32_16x16x128_f8f6f4 v[44:47], v[24:31], v[206:213], 0, v240, v240 op_sel_hi:[0,0,0]
	v_mfma_scale_f32_16x16x128_f8f6f4 v[40:43], v[16:23], v[206:213], 0, v240, v240 op_sel_hi:[0,0,0]
	s_setprio 0
	s_setprio 1
	v_mfma_scale_f32_16x16x128_f8f6f4 v[84:87], v[8:15], v[164:171], 0, v240, v240 op_sel_hi:[0,0,0]
	v_mfma_scale_f32_16x16x128_f8f6f4 v[80:83], v[0:7], v[164:171], 0, v240, v240 op_sel_hi:[0,0,0]
	v_mfma_scale_f32_16x16x128_f8f6f4 v[68:71], v[8:15], v[172:179], 0, v240, v240 op_sel_hi:[0,0,0]
	v_mfma_scale_f32_16x16x128_f8f6f4 v[64:67], v[0:7], v[172:179], 0, v240, v240 op_sel_hi:[0,0,0]
	v_mfma_scale_f32_16x16x128_f8f6f4 v[52:55], v[8:15], v[198:205], 0, v240, v240 op_sel_hi:[0,0,0]
	v_mfma_scale_f32_16x16x128_f8f6f4 v[48:51], v[0:7], v[198:205], 0, v240, v240 op_sel_hi:[0,0,0]
	v_mfma_scale_f32_16x16x128_f8f6f4 v[36:39], v[8:15], v[206:213], 0, v240, v240 op_sel_hi:[0,0,0]
	v_mfma_scale_f32_16x16x128_f8f6f4 v[32:35], v[0:7], v[206:213], 0, v240, v240 op_sel_hi:[0,0,0]
	s_setprio 0
	s_barrier
	s_add_i32 s14, 0, 0x18000
	s_add_i32 s15, 0, 0x1c000
	v_add_u32_e32 v12, s14, v221
	v_add_u32_e32 v28, s15, v221
	ds_read_b128 v[0:3], v12
	ds_read_b128 v[4:7], v12 offset:1024
	ds_read_b128 v[8:11], v12 offset:2048
	ds_read_b128 v[12:15], v12 offset:3072
	ds_read_b128 v[16:19], v28
	ds_read_b128 v[20:23], v28 offset:1024
	ds_read_b128 v[24:27], v28 offset:2048
	ds_read_b128 v[28:31], v28 offset:3072
	s_mov_b32 m0, s25
	v_lshl_add_u64 v[180:181], v[162:163], 0, s[2:3]
	ds_read_b128 v[164:167], v223 offset:32768
	ds_read_b128 v[168:171], v223 offset:33792
	ds_read_b128 v[172:175], v223 offset:34816
	ds_read_b128 v[176:179], v223 offset:35840
	ds_read_b128 v[198:201], v223 offset:36864
	ds_read_b128 v[202:205], v223 offset:37888
	ds_read_b128 v[206:209], v223 offset:38912
	ds_read_b128 v[210:213], v223 offset:39936
	global_load_lds_dwordx4 v[180:181], off
	v_lshl_add_u64 v[180:181], v[162:163], 0, s[82:83]
	s_mov_b32 m0, s26
	s_nop 0
	global_load_lds_dwordx4 v[180:181], off
	s_waitcnt vmcnt(8)
	s_waitcnt lgkmcnt(0)
	s_barrier
	s_setprio 1
	s_waitcnt lgkmcnt(0)
	v_mfma_scale_f32_16x16x128_f8f6f4 v[156:159], v[0:7], v[164:171], v[156:159], v240, v240 op_sel_hi:[0,0,0]
	v_mfma_scale_f32_16x16x128_f8f6f4 v[152:155], v[8:15], v[164:171], v[152:155], v240, v240 op_sel_hi:[0,0,0]
	v_mfma_scale_f32_16x16x128_f8f6f4 v[140:143], v[0:7], v[172:179], v[140:143], v240, v240 op_sel_hi:[0,0,0]
	v_mfma_scale_f32_16x16x128_f8f6f4 v[136:139], v[8:15], v[172:179], v[136:139], v240, v240 op_sel_hi:[0,0,0]
	v_mfma_scale_f32_16x16x128_f8f6f4 v[124:127], v[0:7], v[198:205], v[124:127], v240, v240 op_sel_hi:[0,0,0]
	v_mfma_scale_f32_16x16x128_f8f6f4 v[120:123], v[8:15], v[198:205], v[120:123], v240, v240 op_sel_hi:[0,0,0]
	v_mfma_scale_f32_16x16x128_f8f6f4 v[108:111], v[0:7], v[206:213], v[108:111], v240, v240 op_sel_hi:[0,0,0]
	v_mfma_scale_f32_16x16x128_f8f6f4 v[104:107], v[8:15], v[206:213], v[104:107], v240, v240 op_sel_hi:[0,0,0]
	s_setprio 0
	s_setprio 1
	v_mfma_scale_f32_16x16x128_f8f6f4 v[148:151], v[16:23], v[164:171], v[148:151], v240, v240 op_sel_hi:[0,0,0]
	v_mfma_scale_f32_16x16x128_f8f6f4 v[144:147], v[24:31], v[164:171], v[144:147], v240, v240 op_sel_hi:[0,0,0]
	v_mfma_scale_f32_16x16x128_f8f6f4 v[132:135], v[16:23], v[172:179], v[132:135], v240, v240 op_sel_hi:[0,0,0]
	v_mfma_scale_f32_16x16x128_f8f6f4 v[128:131], v[24:31], v[172:179], v[128:131], v240, v240 op_sel_hi:[0,0,0]
	v_mfma_scale_f32_16x16x128_f8f6f4 v[116:119], v[16:23], v[198:205], v[116:119], v240, v240 op_sel_hi:[0,0,0]
	v_mfma_scale_f32_16x16x128_f8f6f4 v[112:115], v[24:31], v[198:205], v[112:115], v240, v240 op_sel_hi:[0,0,0]
	v_mfma_scale_f32_16x16x128_f8f6f4 v[100:103], v[16:23], v[206:213], v[100:103], v240, v240 op_sel_hi:[0,0,0]
	v_mfma_scale_f32_16x16x128_f8f6f4 v[96:99], v[24:31], v[206:213], v[96:99], v240, v240 op_sel_hi:[0,0,0]
	s_setprio 0
	s_barrier
	s_add_i32 s14, s14, s6
	v_lshl_add_u64 v[180:181], v[160:161], 0, s[56:57]
	s_mov_b32 m0, s14
	ds_read_b128 v[164:167], v223 offset:49152
	ds_read_b128 v[168:171], v223 offset:50176
	ds_read_b128 v[172:175], v223 offset:51200
	ds_read_b128 v[176:179], v223 offset:52224
	ds_read_b128 v[198:201], v223 offset:53248
	ds_read_b128 v[202:205], v223 offset:54272
	ds_read_b128 v[206:209], v223 offset:55296
	ds_read_b128 v[210:213], v223 offset:56320
	global_load_lds_dwordx4 v[180:181], off
	v_lshl_add_u64 v[180:181], v[160:161], 0, s[80:81]
	s_add_i32 m0, s14, 0x2000
	s_add_i32 s14, s15, s6
	global_load_lds_dwordx4 v[180:181], off
	v_lshl_add_u64 v[180:181], v[160:161], 0, s[74:75]
	s_mov_b32 m0, s14
	v_lshl_add_u64 v[160:161], v[160:161], 0, s[62:63]
	global_load_lds_dwordx4 v[180:181], off
	s_add_i32 m0, s14, 0x2000
	s_nop 0
	global_load_lds_dwordx4 v[160:161], off
	v_lshl_add_u64 v[160:161], v[162:163], 0, s[56:57]
	s_mov_b32 m0, s28
	s_nop 0
	global_load_lds_dwordx4 v[160:161], off
	v_lshl_add_u64 v[160:161], v[162:163], 0, s[80:81]
	s_mov_b32 m0, s29
	s_nop 0
	global_load_lds_dwordx4 v[160:161], off
	s_waitcnt vmcnt(8)
	s_waitcnt lgkmcnt(0)
	s_barrier
	s_setprio 1
	s_waitcnt lgkmcnt(0)
	v_mfma_scale_f32_16x16x128_f8f6f4 v[92:95], v[0:7], v[164:171], v[92:95], v240, v240 op_sel_hi:[0,0,0]
	v_mfma_scale_f32_16x16x128_f8f6f4 v[88:91], v[8:15], v[164:171], v[88:91], v240, v240 op_sel_hi:[0,0,0]
	v_mfma_scale_f32_16x16x128_f8f6f4 v[76:79], v[0:7], v[172:179], v[76:79], v240, v240 op_sel_hi:[0,0,0]
	v_mfma_scale_f32_16x16x128_f8f6f4 v[72:75], v[8:15], v[172:179], v[72:75], v240, v240 op_sel_hi:[0,0,0]
	v_mfma_scale_f32_16x16x128_f8f6f4 v[60:63], v[0:7], v[198:205], v[60:63], v240, v240 op_sel_hi:[0,0,0]
	v_mfma_scale_f32_16x16x128_f8f6f4 v[56:59], v[8:15], v[198:205], v[56:59], v240, v240 op_sel_hi:[0,0,0]
	v_mfma_scale_f32_16x16x128_f8f6f4 v[44:47], v[0:7], v[206:213], v[44:47], v240, v240 op_sel_hi:[0,0,0]
	v_mfma_scale_f32_16x16x128_f8f6f4 v[40:43], v[8:15], v[206:213], v[40:43], v240, v240 op_sel_hi:[0,0,0]
	s_setprio 0
	s_setprio 1
	v_mfma_scale_f32_16x16x128_f8f6f4 v[84:87], v[16:23], v[164:171], v[84:87], v240, v240 op_sel_hi:[0,0,0]
	v_mfma_scale_f32_16x16x128_f8f6f4 v[80:83], v[24:31], v[164:171], v[80:83], v240, v240 op_sel_hi:[0,0,0]
	v_mfma_scale_f32_16x16x128_f8f6f4 v[68:71], v[16:23], v[172:179], v[68:71], v240, v240 op_sel_hi:[0,0,0]
	v_mfma_scale_f32_16x16x128_f8f6f4 v[64:67], v[24:31], v[172:179], v[64:67], v240, v240 op_sel_hi:[0,0,0]
	v_mfma_scale_f32_16x16x128_f8f6f4 v[52:55], v[16:23], v[198:205], v[52:55], v240, v240 op_sel_hi:[0,0,0]
	v_mfma_scale_f32_16x16x128_f8f6f4 v[48:51], v[24:31], v[198:205], v[48:51], v240, v240 op_sel_hi:[0,0,0]
	v_mfma_scale_f32_16x16x128_f8f6f4 v[36:39], v[16:23], v[206:213], v[36:39], v240, v240 op_sel_hi:[0,0,0]
	v_mfma_scale_f32_16x16x128_f8f6f4 v[32:35], v[24:31], v[206:213], v[32:35], v240, v240 op_sel_hi:[0,0,0]
	s_setprio 0
	s_barrier
	s_add_i32 s85, s85, 2
	s_add_u32 s50, s50, 0x100
	s_addc_u32 s51, s51, 0
	s_add_u32 s70, s70, 0x100
	s_addc_u32 s84, s84, 0
	s_cmp_gt_u32 s85, 19

.LBB0_361:
	s_add_u32 vcc_lo, s16, 0x80
	s_addc_u32 vcc_hi, s17, 0
	s_add_u32 s16, s14, 0x100
	s_addc_u32 s17, s15, 0
	s_mov_b32 s14, 0
	s_add_i32 s24, s14, 2
	s_add_u32 s46, vcc_lo, 0x80
	s_addc_u32 s15, vcc_hi, 0
	s_add_i32 s18, 0, 0x10000
	s_cmp_eq_u32 s6, s14
	s_cselect_b32 s15, s1, s15
	s_cselect_b32 s14, s0, s46
	s_cselect_b32 s47, s13, s17
	s_cselect_b32 s46, s12, s16
	s_add_i32 s21, 0, 0x14000
	v_add_u32_e32 v140, s18, v223
	v_add_u32_e32 v156, s21, v223
	s_waitcnt lgkmcnt(0)
	ds_read_b128 v[128:131], v140
	ds_read_b128 v[132:135], v140 offset:1024
	ds_read_b128 v[136:139], v140 offset:2048
	ds_read_b128 v[140:143], v140 offset:3072
	ds_read_b128 v[144:147], v156
	ds_read_b128 v[148:151], v156 offset:1024
	ds_read_b128 v[152:155], v156 offset:2048
	ds_read_b128 v[156:159], v156 offset:3072
	v_lshl_add_u64 v[186:187], vcc, 0, v[196:197]
	s_add_i32 m0, s28, 0xc000
	ds_read_b128 v[160:163], v225
	ds_read_b128 v[164:167], v225 offset:1024
	ds_read_b128 v[168:171], v225 offset:2048
	ds_read_b128 v[172:175], v225 offset:3072
	ds_read_b128 v[176:179], v225 offset:4096
	ds_read_b128 v[180:183], v225 offset:5120
	ds_read_b128 v[200:203], v225 offset:6144
	ds_read_b128 v[204:207], v225 offset:7168
	global_load_lds_dwordx4 v[186:187], off
	v_lshl_add_u64 v[186:187], vcc, 0, v[198:199]
	s_add_i32 m0, s28, 0xe000
	s_nop 0
	global_load_lds_dwordx4 v[186:187], off
	s_waitcnt vmcnt(8)
	s_waitcnt lgkmcnt(0)
	s_barrier
	s_setprio 1
	s_waitcnt lgkmcnt(0)
	v_mfma_f32_16x16x32_bf16 v[124:127], v[128:131], v[160:163], 0
	v_mfma_f32_16x16x32_bf16 v[120:123], v[136:139], v[160:163], 0
	v_mfma_f32_16x16x32_bf16 v[108:111], v[128:131], v[168:171], 0
	v_mfma_f32_16x16x32_bf16 v[104:107], v[136:139], v[168:171], 0
	v_mfma_f32_16x16x32_bf16 v[92:95], v[128:131], v[176:179], 0
	v_mfma_f32_16x16x32_bf16 v[88:91], v[136:139], v[176:179], 0
	v_mfma_f32_16x16x32_bf16 v[76:79], v[128:131], v[200:203], 0
	v_mfma_f32_16x16x32_bf16 v[72:75], v[136:139], v[200:203], 0
	v_mfma_f32_16x16x32_bf16 v[124:127], v[132:135], v[164:167], v[124:127]
	v_mfma_f32_16x16x32_bf16 v[120:123], v[140:143], v[164:167], v[120:123]
	v_mfma_f32_16x16x32_bf16 v[108:111], v[132:135], v[172:175], v[108:111]
	v_mfma_f32_16x16x32_bf16 v[104:107], v[140:143], v[172:175], v[104:107]
	v_mfma_f32_16x16x32_bf16 v[92:95], v[132:135], v[180:183], v[92:95]
	v_mfma_f32_16x16x32_bf16 v[88:91], v[140:143], v[180:183], v[88:91]
	v_mfma_f32_16x16x32_bf16 v[76:79], v[132:135], v[204:207], v[76:79]
	v_mfma_f32_16x16x32_bf16 v[72:75], v[140:143], v[204:207], v[72:75]
	s_setprio 0
	s_setprio 1
	v_mfma_f32_16x16x32_bf16 v[116:119], v[144:147], v[160:163], 0
	v_mfma_f32_16x16x32_bf16 v[112:115], v[152:155], v[160:163], 0
	v_mfma_f32_16x16x32_bf16 v[100:103], v[144:147], v[168:171], 0
	v_mfma_f32_16x16x32_bf16 v[96:99], v[152:155], v[168:171], 0
	v_mfma_f32_16x16x32_bf16 v[84:87], v[144:147], v[176:179], 0
	v_mfma_f32_16x16x32_bf16 v[80:83], v[152:155], v[176:179], 0
	v_mfma_f32_16x16x32_bf16 v[68:71], v[144:147], v[200:203], 0
	v_mfma_f32_16x16x32_bf16 v[64:67], v[152:155], v[200:203], 0
	v_mfma_f32_16x16x32_bf16 v[116:119], v[148:151], v[164:167], v[116:119]
	v_mfma_f32_16x16x32_bf16 v[112:115], v[156:159], v[164:167], v[112:115]
	v_mfma_f32_16x16x32_bf16 v[100:103], v[148:151], v[172:175], v[100:103]
	v_mfma_f32_16x16x32_bf16 v[96:99], v[156:159], v[172:175], v[96:99]
	v_mfma_f32_16x16x32_bf16 v[84:87], v[148:151], v[180:183], v[84:87]
	v_mfma_f32_16x16x32_bf16 v[80:83], v[156:159], v[180:183], v[80:83]
	v_mfma_f32_16x16x32_bf16 v[68:71], v[148:151], v[204:207], v[68:71]
	v_mfma_f32_16x16x32_bf16 v[64:67], v[156:159], v[204:207], v[64:67]
	s_setprio 0
	s_barrier
	s_add_i32 s18, s18, s27
	v_lshl_add_u64 v[186:187], s[46:47], 0, v[184:185]
	s_mov_b32 m0, s18
	ds_read_b128 v[160:163], v225 offset:16384
	ds_read_b128 v[164:167], v225 offset:17408
	ds_read_b128 v[168:171], v225 offset:18432
	ds_read_b128 v[172:175], v225 offset:19456
	ds_read_b128 v[176:179], v225 offset:20480
	ds_read_b128 v[180:183], v225 offset:21504
	ds_read_b128 v[200:203], v225 offset:22528
	ds_read_b128 v[204:207], v225 offset:23552
	global_load_lds_dwordx4 v[186:187], off
	s_add_i32 m0, s18, 0x2000
	s_add_u32 s46, s46, s44
	v_lshl_add_u64 v[188:189], v[186:187], 0, s[70:71]
	s_addc_u32 s47, s47, 0
	s_add_i32 s18, s21, s27
	global_load_lds_dwordx4 v[188:189], off
	v_lshl_add_u64 v[208:209], s[46:47], 0, v[184:185]
	s_mov_b32 m0, s18
	v_lshl_add_u64 v[210:211], v[208:209], 0, s[70:71]
	global_load_lds_dwordx4 v[208:209], off
	s_add_i32 m0, s18, 0x2000
	v_lshl_add_u64 v[212:213], s[14:15], 0, v[194:195]
	global_load_lds_dwordx4 v[210:211], off
	s_mov_b32 m0, s28
	v_lshl_add_u64 v[214:215], v[212:213], 0, s[70:71]
	global_load_lds_dwordx4 v[212:213], off
	s_mov_b32 m0, s29
	s_nop 0
	global_load_lds_dwordx4 v[214:215], off
	s_waitcnt vmcnt(8)
	s_waitcnt lgkmcnt(0)
	s_barrier
	s_setprio 1
	s_waitcnt lgkmcnt(0)
	v_mfma_f32_16x16x32_bf16 v[60:63], v[128:131], v[160:163], 0
	v_mfma_f32_16x16x32_bf16 v[56:59], v[136:139], v[160:163], 0
	v_mfma_f32_16x16x32_bf16 v[44:47], v[128:131], v[168:171], 0
	v_mfma_f32_16x16x32_bf16 v[40:43], v[136:139], v[168:171], 0
	v_mfma_f32_16x16x32_bf16 v[28:31], v[128:131], v[176:179], 0
	v_mfma_f32_16x16x32_bf16 v[24:27], v[136:139], v[176:179], 0
	v_mfma_f32_16x16x32_bf16 v[12:15], v[128:131], v[200:203], 0
	v_mfma_f32_16x16x32_bf16 v[8:11], v[136:139], v[200:203], 0
	v_mfma_f32_16x16x32_bf16 v[60:63], v[132:135], v[164:167], v[60:63]
	v_mfma_f32_16x16x32_bf16 v[56:59], v[140:143], v[164:167], v[56:59]
	v_mfma_f32_16x16x32_bf16 v[44:47], v[132:135], v[172:175], v[44:47]
	v_mfma_f32_16x16x32_bf16 v[40:43], v[140:143], v[172:175], v[40:43]
	v_mfma_f32_16x16x32_bf16 v[28:31], v[132:135], v[180:183], v[28:31]
	v_mfma_f32_16x16x32_bf16 v[24:27], v[140:143], v[180:183], v[24:27]
	v_mfma_f32_16x16x32_bf16 v[12:15], v[132:135], v[204:207], v[12:15]
	v_mfma_f32_16x16x32_bf16 v[8:11], v[140:143], v[204:207], v[8:11]
	s_setprio 0
	s_setprio 1
	v_mfma_f32_16x16x32_bf16 v[52:55], v[144:147], v[160:163], 0
	v_mfma_f32_16x16x32_bf16 v[48:51], v[152:155], v[160:163], 0
	v_mfma_f32_16x16x32_bf16 v[36:39], v[144:147], v[168:171], 0
	v_mfma_f32_16x16x32_bf16 v[32:35], v[152:155], v[168:171], 0
	v_mfma_f32_16x16x32_bf16 v[20:23], v[144:147], v[176:179], 0
	v_mfma_f32_16x16x32_bf16 v[16:19], v[152:155], v[176:179], 0
	v_mfma_f32_16x16x32_bf16 v[4:7], v[144:147], v[200:203], 0
	v_mfma_f32_16x16x32_bf16 v[0:3], v[152:155], v[200:203], 0
	v_mfma_f32_16x16x32_bf16 v[52:55], v[148:151], v[164:167], v[52:55]
	v_mfma_f32_16x16x32_bf16 v[48:51], v[156:159], v[164:167], v[48:51]
	v_mfma_f32_16x16x32_bf16 v[36:39], v[148:151], v[172:175], v[36:39]
	v_mfma_f32_16x16x32_bf16 v[32:35], v[156:159], v[172:175], v[32:35]
	v_mfma_f32_16x16x32_bf16 v[20:23], v[148:151], v[180:183], v[20:23]
	v_mfma_f32_16x16x32_bf16 v[16:19], v[156:159], v[180:183], v[16:19]
	v_mfma_f32_16x16x32_bf16 v[4:7], v[148:151], v[204:207], v[4:7]
	v_mfma_f32_16x16x32_bf16 v[0:3], v[156:159], v[204:207], v[0:3]
	s_setprio 0
	s_barrier
	s_add_i32 s18, 0, 0x18000
	s_add_i32 s21, 0, 0x1c000
	v_add_u32_e32 v140, s18, v223
	v_add_u32_e32 v156, s21, v223
	ds_read_b128 v[128:131], v140
	ds_read_b128 v[132:135], v140 offset:1024
	ds_read_b128 v[136:139], v140 offset:2048
	ds_read_b128 v[140:143], v140 offset:3072
	ds_read_b128 v[144:147], v156
	ds_read_b128 v[148:151], v156 offset:1024
	ds_read_b128 v[152:155], v156 offset:2048
	ds_read_b128 v[156:159], v156 offset:3072
	s_add_u32 s14, s14, s44
	s_addc_u32 s15, s15, 0
	s_mov_b32 m0, s30
	v_lshl_add_u64 v[216:217], s[14:15], 0, v[194:195]
	ds_read_b128 v[160:163], v225 offset:32768
	ds_read_b128 v[164:167], v225 offset:33792
	ds_read_b128 v[168:171], v225 offset:34816
	ds_read_b128 v[172:175], v225 offset:35840
	ds_read_b128 v[176:179], v225 offset:36864
	ds_read_b128 v[180:183], v225 offset:37888
	ds_read_b128 v[200:203], v225 offset:38912
	ds_read_b128 v[204:207], v225 offset:39936
	global_load_lds_dwordx4 v[216:217], off
	v_lshl_add_u64 v[216:217], v[216:217], 0, s[70:71]
	s_mov_b32 m0, s31
	s_nop 0
	global_load_lds_dwordx4 v[216:217], off
	s_waitcnt vmcnt(8)
	s_waitcnt lgkmcnt(0)
	s_barrier
	s_setprio 1
	s_waitcnt lgkmcnt(0)
	v_mfma_f32_16x16x32_bf16 v[124:127], v[128:131], v[160:163], v[124:127]
	v_mfma_f32_16x16x32_bf16 v[120:123], v[136:139], v[160:163], v[120:123]
	v_mfma_f32_16x16x32_bf16 v[108:111], v[128:131], v[168:171], v[108:111]
	v_mfma_f32_16x16x32_bf16 v[104:107], v[136:139], v[168:171], v[104:107]
	v_mfma_f32_16x16x32_bf16 v[92:95], v[128:131], v[176:179], v[92:95]
	v_mfma_f32_16x16x32_bf16 v[88:91], v[136:139], v[176:179], v[88:91]
	v_mfma_f32_16x16x32_bf16 v[76:79], v[128:131], v[200:203], v[76:79]
	v_mfma_f32_16x16x32_bf16 v[72:75], v[136:139], v[200:203], v[72:75]
	v_mfma_f32_16x16x32_bf16 v[124:127], v[132:135], v[164:167], v[124:127]
	v_mfma_f32_16x16x32_bf16 v[120:123], v[140:143], v[164:167], v[120:123]
	v_mfma_f32_16x16x32_bf16 v[108:111], v[132:135], v[172:175], v[108:111]
	v_mfma_f32_16x16x32_bf16 v[104:107], v[140:143], v[172:175], v[104:107]
	v_mfma_f32_16x16x32_bf16 v[92:95], v[132:135], v[180:183], v[92:95]
	v_mfma_f32_16x16x32_bf16 v[88:91], v[140:143], v[180:183], v[88:91]
	v_mfma_f32_16x16x32_bf16 v[76:79], v[132:135], v[204:207], v[76:79]
	v_mfma_f32_16x16x32_bf16 v[72:75], v[140:143], v[204:207], v[72:75]
	s_setprio 0
	s_setprio 1
	v_mfma_f32_16x16x32_bf16 v[116:119], v[144:147], v[160:163], v[116:119]
	v_mfma_f32_16x16x32_bf16 v[112:115], v[152:155], v[160:163], v[112:115]
	v_mfma_f32_16x16x32_bf16 v[100:103], v[144:147], v[168:171], v[100:103]
	v_mfma_f32_16x16x32_bf16 v[96:99], v[152:155], v[168:171], v[96:99]
	v_mfma_f32_16x16x32_bf16 v[84:87], v[144:147], v[176:179], v[84:87]
	v_mfma_f32_16x16x32_bf16 v[80:83], v[152:155], v[176:179], v[80:83]
	v_mfma_f32_16x16x32_bf16 v[68:71], v[144:147], v[200:203], v[68:71]
	v_mfma_f32_16x16x32_bf16 v[64:67], v[152:155], v[200:203], v[64:67]
	v_mfma_f32_16x16x32_bf16 v[116:119], v[148:151], v[164:167], v[116:119]
	v_mfma_f32_16x16x32_bf16 v[112:115], v[156:159], v[164:167], v[112:115]
	v_mfma_f32_16x16x32_bf16 v[100:103], v[148:151], v[172:175], v[100:103]
	v_mfma_f32_16x16x32_bf16 v[96:99], v[156:159], v[172:175], v[96:99]
	v_mfma_f32_16x16x32_bf16 v[84:87], v[148:151], v[180:183], v[84:87]
	v_mfma_f32_16x16x32_bf16 v[80:83], v[156:159], v[180:183], v[80:83]
	v_mfma_f32_16x16x32_bf16 v[68:71], v[148:151], v[204:207], v[68:71]
	v_mfma_f32_16x16x32_bf16 v[64:67], v[156:159], v[204:207], v[64:67]
	s_setprio 0
	s_barrier
	s_add_i32 s14, s18, s27
	v_lshl_add_u64 v[186:187], v[186:187], 0, s[56:57]
	s_mov_b32 m0, s14
	ds_read_b128 v[160:163], v225 offset:49152
	ds_read_b128 v[164:167], v225 offset:50176
	ds_read_b128 v[168:171], v225 offset:51200
	ds_read_b128 v[172:175], v225 offset:52224
	ds_read_b128 v[176:179], v225 offset:53248
	ds_read_b128 v[180:183], v225 offset:54272
	ds_read_b128 v[200:203], v225 offset:55296
	ds_read_b128 v[204:207], v225 offset:56320
	global_load_lds_dwordx4 v[186:187], off
	v_lshl_add_u64 v[186:187], v[188:189], 0, s[56:57]
	s_add_i32 m0, s14, 0x2000
	s_add_i32 s14, s21, s27
	global_load_lds_dwordx4 v[186:187], off
	v_lshl_add_u64 v[186:187], v[208:209], 0, s[56:57]
	s_mov_b32 m0, s14
	s_nop 0
	global_load_lds_dwordx4 v[186:187], off
	v_lshl_add_u64 v[186:187], v[210:211], 0, s[56:57]
	s_add_i32 m0, s14, 0x2000
	s_nop 0
	global_load_lds_dwordx4 v[186:187], off
	v_lshl_add_u64 v[186:187], v[212:213], 0, s[56:57]
	s_mov_b32 m0, s19
	s_nop 0
	global_load_lds_dwordx4 v[186:187], off
	v_lshl_add_u64 v[186:187], v[214:215], 0, s[56:57]
	s_mov_b32 m0, s20
	s_nop 0
	global_load_lds_dwordx4 v[186:187], off
	s_waitcnt vmcnt(8)
	s_waitcnt lgkmcnt(0)
	s_barrier
	s_setprio 1
	s_waitcnt lgkmcnt(0)
	v_mfma_f32_16x16x32_bf16 v[60:63], v[128:131], v[160:163], v[60:63]
	v_mfma_f32_16x16x32_bf16 v[56:59], v[136:139], v[160:163], v[56:59]
	v_mfma_f32_16x16x32_bf16 v[44:47], v[128:131], v[168:171], v[44:47]
	v_mfma_f32_16x16x32_bf16 v[40:43], v[136:139], v[168:171], v[40:43]
	v_mfma_f32_16x16x32_bf16 v[28:31], v[128:131], v[176:179], v[28:31]
	v_mfma_f32_16x16x32_bf16 v[24:27], v[136:139], v[176:179], v[24:27]
	v_mfma_f32_16x16x32_bf16 v[12:15], v[128:131], v[200:203], v[12:15]
	v_mfma_f32_16x16x32_bf16 v[8:11], v[136:139], v[200:203], v[8:11]
	v_mfma_f32_16x16x32_bf16 v[60:63], v[132:135], v[164:167], v[60:63]
	v_mfma_f32_16x16x32_bf16 v[56:59], v[140:143], v[164:167], v[56:59]
	v_mfma_f32_16x16x32_bf16 v[44:47], v[132:135], v[172:175], v[44:47]
	v_mfma_f32_16x16x32_bf16 v[40:43], v[140:143], v[172:175], v[40:43]
	v_mfma_f32_16x16x32_bf16 v[28:31], v[132:135], v[180:183], v[28:31]
	v_mfma_f32_16x16x32_bf16 v[24:27], v[140:143], v[180:183], v[24:27]
	v_mfma_f32_16x16x32_bf16 v[12:15], v[132:135], v[204:207], v[12:15]
	v_mfma_f32_16x16x32_bf16 v[8:11], v[140:143], v[204:207], v[8:11]
	s_setprio 0
	s_setprio 1
	v_mfma_f32_16x16x32_bf16 v[52:55], v[144:147], v[160:163], v[52:55]
	v_mfma_f32_16x16x32_bf16 v[48:51], v[152:155], v[160:163], v[48:51]
	v_mfma_f32_16x16x32_bf16 v[36:39], v[144:147], v[168:171], v[36:39]
	v_mfma_f32_16x16x32_bf16 v[32:35], v[152:155], v[168:171], v[32:35]
	v_mfma_f32_16x16x32_bf16 v[20:23], v[144:147], v[176:179], v[20:23]
	v_mfma_f32_16x16x32_bf16 v[16:19], v[152:155], v[176:179], v[16:19]
	v_mfma_f32_16x16x32_bf16 v[4:7], v[144:147], v[200:203], v[4:7]
	v_mfma_f32_16x16x32_bf16 v[0:3], v[152:155], v[200:203], v[0:3]
	v_mfma_f32_16x16x32_bf16 v[52:55], v[148:151], v[164:167], v[52:55]
	v_mfma_f32_16x16x32_bf16 v[48:51], v[156:159], v[164:167], v[48:51]
	v_mfma_f32_16x16x32_bf16 v[36:39], v[148:151], v[172:175], v[36:39]
	v_mfma_f32_16x16x32_bf16 v[32:35], v[156:159], v[172:175], v[32:35]
	v_mfma_f32_16x16x32_bf16 v[20:23], v[148:151], v[180:183], v[20:23]
	v_mfma_f32_16x16x32_bf16 v[16:19], v[156:159], v[180:183], v[16:19]
	v_mfma_f32_16x16x32_bf16 v[4:7], v[148:151], v[204:207], v[4:7]
	v_mfma_f32_16x16x32_bf16 v[0:3], v[156:159], v[204:207], v[0:3]
	s_setprio 0
	s_barrier
	s_add_u32 vcc_lo, vcc_lo, 0x100
	s_addc_u32 vcc_hi, vcc_hi, 0
	s_add_u32 s16, s16, 0x100
	s_addc_u32 s17, s17, 0
	s_cmp_ge_u32 s24, s84
	s_mov_b32 s14, s24

.LBB0_421:
	s_add_u32 s44, s16, 0x80
	s_addc_u32 s45, s17, 0
	s_add_u32 s16, s14, 0x100
	s_addc_u32 s17, s15, 0
	s_mov_b32 s14, 0
	s_waitcnt lgkmcnt(0)
	s_add_i32 s23, s14, 2
	s_add_u32 s24, s44, 0x80
	s_addc_u32 s15, s45, 0
	s_add_i32 s49, 0, 0x10000
	s_cmp_eq_u32 s31, s14
	s_cselect_b32 s15, s1, s15
	s_cselect_b32 s14, s0, s24
	s_cselect_b32 s51, s43, s17
	s_cselect_b32 s50, s42, s16
	s_add_i32 s24, 0, 0x14000
	v_add_u32_e32 v108, s49, v249
	v_add_u32_e32 v140, s24, v249
	ds_read_b128 v[80:83], v108
	ds_read_b128 v[84:87], v108 offset:1024
	ds_read_b128 v[104:107], v108 offset:2048
	ds_read_b128 v[108:111], v108 offset:3072
	ds_read_b128 v[124:127], v140
	ds_read_b128 v[132:135], v140 offset:1024
	ds_read_b128 v[136:139], v140 offset:2048
	ds_read_b128 v[140:143], v140 offset:3072
	v_lshl_add_u64 v[208:209], s[44:45], 0, v[196:197]
	s_add_i32 m0, s20, 0xc000
	ds_read_b128 v[144:147], v251
	ds_read_b128 v[148:151], v251 offset:1024
	ds_read_b128 v[152:155], v251 offset:2048
	ds_read_b128 v[156:159], v251 offset:3072
	ds_read_b128 v[160:163], v251 offset:4096
	ds_read_b128 v[164:167], v251 offset:5120
	ds_read_b128 v[200:203], v251 offset:6144
	ds_read_b128 v[204:207], v251 offset:7168
	global_load_lds_dwordx4 v[208:209], off
	v_lshl_add_u64 v[208:209], s[44:45], 0, v[198:199]
	s_add_i32 m0, s20, 0xe000
	s_nop 0
	global_load_lds_dwordx4 v[208:209], off
	s_waitcnt vmcnt(8)
	s_waitcnt lgkmcnt(0)
	s_barrier
	s_setprio 1
	s_waitcnt lgkmcnt(0)
	v_mfma_f32_16x16x32_bf16 v[180:183], v[80:83], v[144:147], 0
	v_mfma_f32_16x16x32_bf16 v[176:179], v[104:107], v[144:147], 0
	v_mfma_f32_16x16x32_bf16 v[128:131], v[80:83], v[152:155], 0
	v_mfma_f32_16x16x32_bf16 v[120:123], v[104:107], v[152:155], 0
	v_mfma_f32_16x16x32_bf16 v[100:103], v[80:83], v[160:163], 0
	v_mfma_f32_16x16x32_bf16 v[96:99], v[104:107], v[160:163], 0
	v_mfma_f32_16x16x32_bf16 v[76:79], v[80:83], v[200:203], 0
	v_mfma_f32_16x16x32_bf16 v[72:75], v[104:107], v[200:203], 0
	v_mfma_f32_16x16x32_bf16 v[180:183], v[84:87], v[148:151], v[180:183]
	v_mfma_f32_16x16x32_bf16 v[176:179], v[108:111], v[148:151], v[176:179]
	v_mfma_f32_16x16x32_bf16 v[128:131], v[84:87], v[156:159], v[128:131]
	v_mfma_f32_16x16x32_bf16 v[120:123], v[108:111], v[156:159], v[120:123]
	v_mfma_f32_16x16x32_bf16 v[100:103], v[84:87], v[164:167], v[100:103]
	v_mfma_f32_16x16x32_bf16 v[96:99], v[108:111], v[164:167], v[96:99]
	v_mfma_f32_16x16x32_bf16 v[76:79], v[84:87], v[204:207], v[76:79]
	v_mfma_f32_16x16x32_bf16 v[72:75], v[108:111], v[204:207], v[72:75]
	s_setprio 0
	s_setprio 1
	v_mfma_f32_16x16x32_bf16 v[172:175], v[124:127], v[144:147], 0
	v_mfma_f32_16x16x32_bf16 v[116:119], v[124:127], v[152:155], 0
	v_mfma_f32_16x16x32_bf16 v[112:115], v[136:139], v[152:155], 0
	v_mfma_f32_16x16x32_bf16 v[92:95], v[124:127], v[160:163], 0
	v_mfma_f32_16x16x32_bf16 v[88:91], v[136:139], v[160:163], 0
	v_mfma_f32_16x16x32_bf16 v[68:71], v[124:127], v[200:203], 0
	v_mfma_f32_16x16x32_bf16 v[64:67], v[136:139], v[200:203], 0
	v_mfma_f32_16x16x32_bf16 v[172:175], v[132:135], v[148:151], v[172:175]
	v_mfma_f32_16x16x32_bf16 v[144:147], v[136:139], v[144:147], 0
	v_mfma_f32_16x16x32_bf16 v[116:119], v[132:135], v[156:159], v[116:119]
	v_mfma_f32_16x16x32_bf16 v[112:115], v[140:143], v[156:159], v[112:115]
	v_mfma_f32_16x16x32_bf16 v[92:95], v[132:135], v[164:167], v[92:95]
	v_mfma_f32_16x16x32_bf16 v[88:91], v[140:143], v[164:167], v[88:91]
	v_mfma_f32_16x16x32_bf16 v[68:71], v[132:135], v[204:207], v[68:71]
	v_mfma_f32_16x16x32_bf16 v[64:67], v[140:143], v[204:207], v[64:67]
	v_mfma_f32_16x16x32_bf16 v[144:147], v[140:143], v[148:151], v[144:147]
	s_setprio 0
	s_barrier
	s_add_i32 s49, s49, s19
	v_lshl_add_u64 v[212:213], s[50:51], 0, v[184:185]
	s_mov_b32 m0, s49
	ds_read_b128 v[148:151], v251 offset:16384
	ds_read_b128 v[152:155], v251 offset:17408
	ds_read_b128 v[156:159], v251 offset:18432
	ds_read_b128 v[160:163], v251 offset:19456
	ds_read_b128 v[164:167], v251 offset:20480
	ds_read_b128 v[168:171], v251 offset:21504
	ds_read_b128 v[200:203], v251 offset:22528
	ds_read_b128 v[204:207], v251 offset:23552
	global_load_lds_dwordx4 v[212:213], off
	s_add_i32 m0, s49, 0x2000
	s_add_u32 s50, s50, s8
	v_lshl_add_u64 v[214:215], v[212:213], 0, s[70:71]
	s_addc_u32 s51, s51, 0
	s_add_i32 s24, s24, s19
	global_load_lds_dwordx4 v[214:215], off
	v_lshl_add_u64 v[216:217], s[50:51], 0, v[184:185]
	s_mov_b32 m0, s24
	v_lshl_add_u64 v[218:219], v[216:217], 0, s[70:71]
	global_load_lds_dwordx4 v[216:217], off
	s_add_i32 m0, s24, 0x2000
	v_lshl_add_u64 v[220:221], s[14:15], 0, v[194:195]
	global_load_lds_dwordx4 v[218:219], off
	s_mov_b32 m0, s20
	v_lshl_add_u64 v[222:223], v[220:221], 0, s[70:71]
	global_load_lds_dwordx4 v[220:221], off
	s_mov_b32 m0, s25
	s_nop 0
	global_load_lds_dwordx4 v[222:223], off
	s_waitcnt vmcnt(8)
	s_waitcnt lgkmcnt(0)
	s_barrier
	s_setprio 1
	s_waitcnt lgkmcnt(0)
	v_mfma_f32_16x16x32_bf16 v[60:63], v[80:83], v[148:151], 0
	v_mfma_f32_16x16x32_bf16 v[56:59], v[104:107], v[148:151], 0
	v_mfma_f32_16x16x32_bf16 v[44:47], v[80:83], v[156:159], 0
	v_mfma_f32_16x16x32_bf16 v[40:43], v[104:107], v[156:159], 0
	v_mfma_f32_16x16x32_bf16 v[28:31], v[80:83], v[164:167], 0
	v_mfma_f32_16x16x32_bf16 v[24:27], v[104:107], v[164:167], 0
	v_mfma_f32_16x16x32_bf16 v[12:15], v[80:83], v[200:203], 0
	v_mfma_f32_16x16x32_bf16 v[8:11], v[104:107], v[200:203], 0
	v_mfma_f32_16x16x32_bf16 v[60:63], v[84:87], v[152:155], v[60:63]
	v_mfma_f32_16x16x32_bf16 v[56:59], v[108:111], v[152:155], v[56:59]
	v_mfma_f32_16x16x32_bf16 v[44:47], v[84:87], v[160:163], v[44:47]
	v_mfma_f32_16x16x32_bf16 v[40:43], v[108:111], v[160:163], v[40:43]
	v_mfma_f32_16x16x32_bf16 v[28:31], v[84:87], v[168:171], v[28:31]
	v_mfma_f32_16x16x32_bf16 v[24:27], v[108:111], v[168:171], v[24:27]
	v_mfma_f32_16x16x32_bf16 v[12:15], v[84:87], v[204:207], v[12:15]
	v_mfma_f32_16x16x32_bf16 v[8:11], v[108:111], v[204:207], v[8:11]
	s_setprio 0
	s_setprio 1
	v_mfma_f32_16x16x32_bf16 v[52:55], v[124:127], v[148:151], 0
	v_mfma_f32_16x16x32_bf16 v[48:51], v[136:139], v[148:151], 0
	v_mfma_f32_16x16x32_bf16 v[36:39], v[124:127], v[156:159], 0
	v_mfma_f32_16x16x32_bf16 v[32:35], v[136:139], v[156:159], 0
	v_mfma_f32_16x16x32_bf16 v[20:23], v[124:127], v[164:167], 0
	v_mfma_f32_16x16x32_bf16 v[16:19], v[136:139], v[164:167], 0
	v_mfma_f32_16x16x32_bf16 v[4:7], v[124:127], v[200:203], 0
	v_mfma_f32_16x16x32_bf16 v[0:3], v[136:139], v[200:203], 0
	v_mfma_f32_16x16x32_bf16 v[52:55], v[132:135], v[152:155], v[52:55]
	v_mfma_f32_16x16x32_bf16 v[48:51], v[140:143], v[152:155], v[48:51]
	v_mfma_f32_16x16x32_bf16 v[36:39], v[132:135], v[160:163], v[36:39]
	v_mfma_f32_16x16x32_bf16 v[32:35], v[140:143], v[160:163], v[32:35]
	v_mfma_f32_16x16x32_bf16 v[20:23], v[132:135], v[168:171], v[20:23]
	v_mfma_f32_16x16x32_bf16 v[16:19], v[140:143], v[168:171], v[16:19]
	v_mfma_f32_16x16x32_bf16 v[4:7], v[132:135], v[204:207], v[4:7]
	v_mfma_f32_16x16x32_bf16 v[0:3], v[140:143], v[204:207], v[0:3]
	s_setprio 0
	s_barrier
	s_add_i32 s24, 0, 0x18000
	s_add_i32 s49, 0, 0x1c000
	v_add_u32_e32 v108, s24, v249
	v_add_u32_e32 v140, s49, v249
	ds_read_b128 v[80:83], v108
	ds_read_b128 v[84:87], v108 offset:1024
	ds_read_b128 v[104:107], v108 offset:2048
	ds_read_b128 v[108:111], v108 offset:3072
	ds_read_b128 v[124:127], v140
	ds_read_b128 v[132:135], v140 offset:1024
	ds_read_b128 v[136:139], v140 offset:2048
	ds_read_b128 v[140:143], v140 offset:3072
	s_add_u32 s14, s14, s8
	s_addc_u32 s15, s15, 0
	s_mov_b32 m0, s26
	v_lshl_add_u64 v[168:169], s[14:15], 0, v[194:195]
	ds_read_b128 v[148:151], v251 offset:32768
	ds_read_b128 v[152:155], v251 offset:33792
	ds_read_b128 v[156:159], v251 offset:34816
	ds_read_b128 v[160:163], v251 offset:35840
	ds_read_b128 v[164:167], v251 offset:36864
	ds_read_b128 v[200:203], v251 offset:37888
	ds_read_b128 v[204:207], v251 offset:38912
	ds_read_b128 v[208:211], v251 offset:39936
	global_load_lds_dwordx4 v[168:169], off
	v_lshl_add_u64 v[168:169], v[168:169], 0, s[70:71]
	s_mov_b32 m0, s27
	s_nop 0
	global_load_lds_dwordx4 v[168:169], off
	s_waitcnt vmcnt(8)
	s_waitcnt lgkmcnt(0)
	s_barrier
	s_setprio 1
	s_waitcnt lgkmcnt(0)
	v_mfma_f32_16x16x32_bf16 v[168:171], v[80:83], v[148:151], v[180:183]
	v_mfma_f32_16x16x32_bf16 v[180:183], v[84:87], v[152:155], v[168:171]
	v_mfma_f32_16x16x32_bf16 v[168:171], v[104:107], v[148:151], v[176:179]
	v_mfma_f32_16x16x32_bf16 v[128:131], v[80:83], v[156:159], v[128:131]
	v_mfma_f32_16x16x32_bf16 v[120:123], v[104:107], v[156:159], v[120:123]
	v_mfma_f32_16x16x32_bf16 v[100:103], v[80:83], v[164:167], v[100:103]
	v_mfma_f32_16x16x32_bf16 v[96:99], v[104:107], v[164:167], v[96:99]
	v_mfma_f32_16x16x32_bf16 v[76:79], v[80:83], v[204:207], v[76:79]
	v_mfma_f32_16x16x32_bf16 v[72:75], v[104:107], v[204:207], v[72:75]
	v_mfma_f32_16x16x32_bf16 v[176:179], v[108:111], v[152:155], v[168:171]
	v_mfma_f32_16x16x32_bf16 v[128:131], v[84:87], v[160:163], v[128:131]
	v_mfma_f32_16x16x32_bf16 v[120:123], v[108:111], v[160:163], v[120:123]
	v_mfma_f32_16x16x32_bf16 v[100:103], v[84:87], v[200:203], v[100:103]
	v_mfma_f32_16x16x32_bf16 v[96:99], v[108:111], v[200:203], v[96:99]
	v_mfma_f32_16x16x32_bf16 v[76:79], v[84:87], v[208:211], v[76:79]
	v_mfma_f32_16x16x32_bf16 v[72:75], v[108:111], v[208:211], v[72:75]
	s_setprio 0
	s_setprio 1
	v_mfma_f32_16x16x32_bf16 v[168:171], v[124:127], v[148:151], v[172:175]
	v_mfma_f32_16x16x32_bf16 v[144:147], v[136:139], v[148:151], v[144:147]
	v_mfma_f32_16x16x32_bf16 v[116:119], v[124:127], v[156:159], v[116:119]
	v_mfma_f32_16x16x32_bf16 v[112:115], v[136:139], v[156:159], v[112:115]
	v_mfma_f32_16x16x32_bf16 v[92:95], v[124:127], v[164:167], v[92:95]
	v_mfma_f32_16x16x32_bf16 v[88:91], v[136:139], v[164:167], v[88:91]
	v_mfma_f32_16x16x32_bf16 v[68:71], v[124:127], v[204:207], v[68:71]
	v_mfma_f32_16x16x32_bf16 v[64:67], v[136:139], v[204:207], v[64:67]
	v_mfma_f32_16x16x32_bf16 v[172:175], v[132:135], v[152:155], v[168:171]
	v_mfma_f32_16x16x32_bf16 v[168:171], v[140:143], v[152:155], v[144:147]
	v_mfma_f32_16x16x32_bf16 v[116:119], v[132:135], v[160:163], v[116:119]
	v_mfma_f32_16x16x32_bf16 v[112:115], v[140:143], v[160:163], v[112:115]
	v_mfma_f32_16x16x32_bf16 v[92:95], v[132:135], v[200:203], v[92:95]
	v_mfma_f32_16x16x32_bf16 v[88:91], v[140:143], v[200:203], v[88:91]
	v_mfma_f32_16x16x32_bf16 v[68:71], v[132:135], v[208:211], v[68:71]
	v_mfma_f32_16x16x32_bf16 v[64:67], v[140:143], v[208:211], v[64:67]
	s_setprio 0
	s_barrier
	s_add_i32 s14, s24, s19
	v_lshl_add_u64 v[208:209], v[212:213], 0, s[56:57]
	s_mov_b32 m0, s14
	ds_read_b128 v[144:147], v251 offset:49152
	ds_read_b128 v[148:151], v251 offset:50176
	ds_read_b128 v[152:155], v251 offset:51200
	ds_read_b128 v[156:159], v251 offset:52224
	ds_read_b128 v[160:163], v251 offset:53248
	ds_read_b128 v[164:167], v251 offset:54272
	ds_read_b128 v[200:203], v251 offset:55296
	ds_read_b128 v[204:207], v251 offset:56320
	global_load_lds_dwordx4 v[208:209], off
	v_lshl_add_u64 v[208:209], v[214:215], 0, s[56:57]
	s_add_i32 m0, s14, 0x2000
	s_add_i32 s14, s49, s19
	global_load_lds_dwordx4 v[208:209], off
	v_lshl_add_u64 v[208:209], v[216:217], 0, s[56:57]
	s_mov_b32 m0, s14
	s_nop 0
	global_load_lds_dwordx4 v[208:209], off
	v_lshl_add_u64 v[208:209], v[218:219], 0, s[56:57]
	s_add_i32 m0, s14, 0x2000
	s_nop 0
	global_load_lds_dwordx4 v[208:209], off
	v_lshl_add_u64 v[208:209], v[220:221], 0, s[56:57]
	s_mov_b32 m0, s29
	s_nop 0
	global_load_lds_dwordx4 v[208:209], off
	v_lshl_add_u64 v[208:209], v[222:223], 0, s[56:57]
	s_mov_b32 m0, s30
	s_nop 0
	global_load_lds_dwordx4 v[208:209], off
	s_waitcnt vmcnt(8)
	s_waitcnt lgkmcnt(0)
	s_barrier
	s_setprio 1
	s_waitcnt lgkmcnt(0)
	v_mfma_f32_16x16x32_bf16 v[60:63], v[80:83], v[144:147], v[60:63]
	v_mfma_f32_16x16x32_bf16 v[56:59], v[104:107], v[144:147], v[56:59]
	v_mfma_f32_16x16x32_bf16 v[44:47], v[80:83], v[152:155], v[44:47]
	v_mfma_f32_16x16x32_bf16 v[40:43], v[104:107], v[152:155], v[40:43]
	v_mfma_f32_16x16x32_bf16 v[28:31], v[80:83], v[160:163], v[28:31]
	v_mfma_f32_16x16x32_bf16 v[24:27], v[104:107], v[160:163], v[24:27]
	v_mfma_f32_16x16x32_bf16 v[12:15], v[80:83], v[200:203], v[12:15]
	v_mfma_f32_16x16x32_bf16 v[8:11], v[104:107], v[200:203], v[8:11]
	v_mfma_f32_16x16x32_bf16 v[60:63], v[84:87], v[148:151], v[60:63]
	v_mfma_f32_16x16x32_bf16 v[56:59], v[108:111], v[148:151], v[56:59]
	v_mfma_f32_16x16x32_bf16 v[44:47], v[84:87], v[156:159], v[44:47]
	v_mfma_f32_16x16x32_bf16 v[40:43], v[108:111], v[156:159], v[40:43]
	v_mfma_f32_16x16x32_bf16 v[28:31], v[84:87], v[164:167], v[28:31]
	v_mfma_f32_16x16x32_bf16 v[24:27], v[108:111], v[164:167], v[24:27]
	v_mfma_f32_16x16x32_bf16 v[12:15], v[84:87], v[204:207], v[12:15]
	v_mfma_f32_16x16x32_bf16 v[8:11], v[108:111], v[204:207], v[8:11]
	s_setprio 0
	s_setprio 1
	v_mfma_f32_16x16x32_bf16 v[52:55], v[124:127], v[144:147], v[52:55]
	v_mfma_f32_16x16x32_bf16 v[48:51], v[136:139], v[144:147], v[48:51]
	v_mfma_f32_16x16x32_bf16 v[36:39], v[124:127], v[152:155], v[36:39]
	v_mfma_f32_16x16x32_bf16 v[32:35], v[136:139], v[152:155], v[32:35]
	v_mfma_f32_16x16x32_bf16 v[20:23], v[124:127], v[160:163], v[20:23]
	v_mfma_f32_16x16x32_bf16 v[16:19], v[136:139], v[160:163], v[16:19]
	v_mfma_f32_16x16x32_bf16 v[4:7], v[124:127], v[200:203], v[4:7]
	v_mfma_f32_16x16x32_bf16 v[0:3], v[136:139], v[200:203], v[0:3]
	v_mfma_f32_16x16x32_bf16 v[52:55], v[132:135], v[148:151], v[52:55]
	v_mfma_f32_16x16x32_bf16 v[48:51], v[140:143], v[148:151], v[48:51]
	v_mfma_f32_16x16x32_bf16 v[36:39], v[132:135], v[156:159], v[36:39]
	v_mfma_f32_16x16x32_bf16 v[32:35], v[140:143], v[156:159], v[32:35]
	v_mfma_f32_16x16x32_bf16 v[20:23], v[132:135], v[164:167], v[20:23]
	v_mfma_f32_16x16x32_bf16 v[16:19], v[140:143], v[164:167], v[16:19]
	v_mfma_f32_16x16x32_bf16 v[4:7], v[132:135], v[204:207], v[4:7]
	v_mfma_f32_16x16x32_bf16 v[0:3], v[140:143], v[204:207], v[0:3]
	s_setprio 0
	s_barrier
	s_add_u32 s44, s44, 0x100
	s_addc_u32 s45, s45, 0
	s_add_u32 s16, s16, 0x100
	s_addc_u32 s17, s17, 0
	s_cmp_ge_u32 s23, s28
	s_mov_b32 s14, s23

.LBB0_458:
	s_ashr_i32 s43, s42, 31
	s_lshl_b64 s[44:45], s[42:43], 19
	s_add_u32 s44, s64, s44
	s_addc_u32 s45, s65, s45
	s_and_b64 s[46:47], s[40:41], exec
	s_cselect_b32 s31, s45, s17
	s_cselect_b32 s43, s44, s16
	s_ashr_i32 s13, s12, 31
	s_lshl_b64 s[46:47], s[12:13], 19
	s_add_u32 s46, s22, s46
	s_addc_u32 s47, s23, s47
	s_and_b64 s[48:49], s[40:41], exec
	s_cselect_b32 s13, s47, s15
	s_cselect_b32 s50, s46, s14
	s_add_u32 s48, s16, 0x40080
	s_addc_u32 s49, s17, 0
	s_add_u32 s16, s14, 0x100
	s_addc_u32 s17, s15, 0
	s_mov_b32 s51, -2
	s_add_u32 s14, s48, 0xfffc0080
	s_addc_u32 s15, s49, -1
	s_add_i32 s70, 0, 0x10000
	s_cmp_eq_u32 s51, 12
	s_cselect_b32 s15, s31, s15
	s_cselect_b32 s14, s43, s14
	v_add_u32_e32 v138, s70, v142
	s_cselect_b32 s61, s13, s17
	s_cselect_b32 s60, s50, s16
	s_add_i32 s84, 0, 0x14000
	ds_read_b128 v[134:137], v138
	ds_read_b128 v[148:151], v138 offset:1024
	ds_read_b128 v[152:155], v138 offset:2048
	ds_read_b128 v[156:159], v138 offset:3072
	v_add_u32_e32 v138, s84, v142
	ds_read_b128 v[160:163], v138
	ds_read_b128 v[164:167], v138 offset:1024
	ds_read_b128 v[168:171], v138 offset:2048
	ds_read_b128 v[172:175], v138 offset:3072
	v_lshl_add_u64 v[138:139], s[48:49], 0, v[132:133]
	s_add_i32 m0, s19, 0xc000
	ds_read_b128 v[176:179], v146
	ds_read_b128 v[180:183], v146 offset:1024
	ds_read_b128 v[194:197], v146 offset:2048
	ds_read_b128 v[198:201], v146 offset:3072
	ds_read_b128 v[202:205], v146 offset:4096
	ds_read_b128 v[206:209], v146 offset:5120
	ds_read_b128 v[210:213], v146 offset:6144
	ds_read_b128 v[214:217], v146 offset:7168
	global_load_lds_dwordx4 v[138:139], off
	v_lshl_add_u64 v[138:139], v[138:139], 0, s[34:35]
	s_add_i32 m0, s19, 0xe000
	s_nop 0
	global_load_lds_dwordx4 v[138:139], off
	s_waitcnt vmcnt(8)
	s_waitcnt lgkmcnt(0)
	s_barrier
	s_setprio 1
	s_waitcnt lgkmcnt(0)
	v_mfma_f32_16x16x32_bf16 v[124:127], v[134:137], v[176:179], 0
	v_mfma_f32_16x16x32_bf16 v[116:119], v[152:155], v[176:179], 0
	v_mfma_f32_16x16x32_bf16 v[108:111], v[134:137], v[194:197], 0
	v_mfma_f32_16x16x32_bf16 v[100:103], v[152:155], v[194:197], 0
	v_mfma_f32_16x16x32_bf16 v[92:95], v[134:137], v[202:205], 0
	v_mfma_f32_16x16x32_bf16 v[84:87], v[152:155], v[202:205], 0
	v_mfma_f32_16x16x32_bf16 v[76:79], v[134:137], v[210:213], 0
	v_mfma_f32_16x16x32_bf16 v[68:71], v[152:155], v[210:213], 0
	v_mfma_f32_16x16x32_bf16 v[124:127], v[148:151], v[180:183], v[124:127]
	v_mfma_f32_16x16x32_bf16 v[116:119], v[156:159], v[180:183], v[116:119]
	v_mfma_f32_16x16x32_bf16 v[108:111], v[148:151], v[198:201], v[108:111]
	v_mfma_f32_16x16x32_bf16 v[100:103], v[156:159], v[198:201], v[100:103]
	v_mfma_f32_16x16x32_bf16 v[92:95], v[148:151], v[206:209], v[92:95]
	v_mfma_f32_16x16x32_bf16 v[84:87], v[156:159], v[206:209], v[84:87]
	v_mfma_f32_16x16x32_bf16 v[76:79], v[148:151], v[214:217], v[76:79]
	v_mfma_f32_16x16x32_bf16 v[68:71], v[156:159], v[214:217], v[68:71]
	s_setprio 0
	s_setprio 1
	v_mfma_f32_16x16x32_bf16 v[120:123], v[160:163], v[176:179], 0
	v_mfma_f32_16x16x32_bf16 v[112:115], v[168:171], v[176:179], 0
	v_mfma_f32_16x16x32_bf16 v[104:107], v[160:163], v[194:197], 0
	v_mfma_f32_16x16x32_bf16 v[96:99], v[168:171], v[194:197], 0
	v_mfma_f32_16x16x32_bf16 v[88:91], v[160:163], v[202:205], 0
	v_mfma_f32_16x16x32_bf16 v[80:83], v[168:171], v[202:205], 0
	v_mfma_f32_16x16x32_bf16 v[72:75], v[160:163], v[210:213], 0
	v_mfma_f32_16x16x32_bf16 v[64:67], v[168:171], v[210:213], 0
	v_mfma_f32_16x16x32_bf16 v[120:123], v[164:167], v[180:183], v[120:123]
	v_mfma_f32_16x16x32_bf16 v[112:115], v[172:175], v[180:183], v[112:115]
	v_mfma_f32_16x16x32_bf16 v[104:107], v[164:167], v[198:201], v[104:107]
	v_mfma_f32_16x16x32_bf16 v[96:99], v[172:175], v[198:201], v[96:99]
	v_mfma_f32_16x16x32_bf16 v[88:91], v[164:167], v[206:209], v[88:91]
	v_mfma_f32_16x16x32_bf16 v[80:83], v[172:175], v[206:209], v[80:83]
	v_mfma_f32_16x16x32_bf16 v[72:75], v[164:167], v[214:217], v[72:75]
	v_mfma_f32_16x16x32_bf16 v[64:67], v[172:175], v[214:217], v[64:67]
	s_setprio 0
	s_barrier
	v_lshl_add_u64 v[138:139], s[60:61], 0, v[184:185]
	s_add_i32 s60, s70, s6
	s_mov_b32 m0, s60
	ds_read_b128 v[176:179], v146 offset:16384
	ds_read_b128 v[180:183], v146 offset:17408
	ds_read_b128 v[194:197], v146 offset:18432
	ds_read_b128 v[198:201], v146 offset:19456
	ds_read_b128 v[202:205], v146 offset:20480
	ds_read_b128 v[206:209], v146 offset:21504
	ds_read_b128 v[210:213], v146 offset:22528
	ds_read_b128 v[214:217], v146 offset:23552
	global_load_lds_dwordx4 v[138:139], off
	v_lshl_add_u64 v[218:219], v[138:139], 0, s[34:35]
	s_add_i32 m0, s60, 0x2000
	s_add_i32 s60, s84, s6
	global_load_lds_dwordx4 v[218:219], off
	v_lshl_add_u64 v[218:219], v[138:139], 0, s[92:93]
	s_mov_b32 m0, s60
	s_nop 0
	global_load_lds_dwordx4 v[218:219], off
	v_lshl_add_u64 v[218:219], v[138:139], 0, s[52:53]
	s_add_i32 m0, s60, 0x2000
	s_nop 0
	global_load_lds_dwordx4 v[218:219], off
	v_lshl_add_u64 v[218:219], s[14:15], 0, v[128:129]
	s_mov_b32 m0, s19
	v_lshl_add_u64 v[220:221], v[218:219], 0, s[34:35]
	global_load_lds_dwordx4 v[218:219], off
	s_mov_b32 m0, s20
	s_nop 0
	global_load_lds_dwordx4 v[220:221], off
	s_waitcnt vmcnt(8)
	s_waitcnt lgkmcnt(0)
	s_barrier
	s_setprio 1
	s_waitcnt lgkmcnt(0)
	v_mfma_f32_16x16x32_bf16 v[60:63], v[134:137], v[176:179], 0
	v_mfma_f32_16x16x32_bf16 v[52:55], v[152:155], v[176:179], 0
	v_mfma_f32_16x16x32_bf16 v[44:47], v[134:137], v[194:197], 0
	v_mfma_f32_16x16x32_bf16 v[36:39], v[152:155], v[194:197], 0
	v_mfma_f32_16x16x32_bf16 v[28:31], v[134:137], v[202:205], 0
	v_mfma_f32_16x16x32_bf16 v[20:23], v[152:155], v[202:205], 0
	v_mfma_f32_16x16x32_bf16 v[12:15], v[134:137], v[210:213], 0
	v_mfma_f32_16x16x32_bf16 v[4:7], v[152:155], v[210:213], 0
	v_mfma_f32_16x16x32_bf16 v[60:63], v[148:151], v[180:183], v[60:63]
	v_mfma_f32_16x16x32_bf16 v[52:55], v[156:159], v[180:183], v[52:55]
	v_mfma_f32_16x16x32_bf16 v[44:47], v[148:151], v[198:201], v[44:47]
	v_mfma_f32_16x16x32_bf16 v[36:39], v[156:159], v[198:201], v[36:39]
	v_mfma_f32_16x16x32_bf16 v[28:31], v[148:151], v[206:209], v[28:31]
	v_mfma_f32_16x16x32_bf16 v[20:23], v[156:159], v[206:209], v[20:23]
	v_mfma_f32_16x16x32_bf16 v[12:15], v[148:151], v[214:217], v[12:15]
	v_mfma_f32_16x16x32_bf16 v[4:7], v[156:159], v[214:217], v[4:7]
	s_setprio 0
	s_setprio 1
	v_mfma_f32_16x16x32_bf16 v[56:59], v[160:163], v[176:179], 0
	v_mfma_f32_16x16x32_bf16 v[48:51], v[168:171], v[176:179], 0
	v_mfma_f32_16x16x32_bf16 v[40:43], v[160:163], v[194:197], 0
	v_mfma_f32_16x16x32_bf16 v[32:35], v[168:171], v[194:197], 0
	v_mfma_f32_16x16x32_bf16 v[24:27], v[160:163], v[202:205], 0
	v_mfma_f32_16x16x32_bf16 v[16:19], v[168:171], v[202:205], 0
	v_mfma_f32_16x16x32_bf16 v[8:11], v[160:163], v[210:213], 0
	v_mfma_f32_16x16x32_bf16 v[0:3], v[168:171], v[210:213], 0
	v_mfma_f32_16x16x32_bf16 v[56:59], v[164:167], v[180:183], v[56:59]
	v_mfma_f32_16x16x32_bf16 v[48:51], v[172:175], v[180:183], v[48:51]
	v_mfma_f32_16x16x32_bf16 v[40:43], v[164:167], v[198:201], v[40:43]
	v_mfma_f32_16x16x32_bf16 v[32:35], v[172:175], v[198:201], v[32:35]
	v_mfma_f32_16x16x32_bf16 v[24:27], v[164:167], v[206:209], v[24:27]
	v_mfma_f32_16x16x32_bf16 v[16:19], v[172:175], v[206:209], v[16:19]
	v_mfma_f32_16x16x32_bf16 v[8:11], v[164:167], v[214:217], v[8:11]
	v_mfma_f32_16x16x32_bf16 v[0:3], v[172:175], v[214:217], v[0:3]
	s_setprio 0
	s_barrier
	s_add_i32 s14, 0, 0x18000
	v_add_u32_e32 v147, s14, v142
	s_add_i32 s15, 0, 0x1c000
	ds_read_b128 v[134:137], v147
	ds_read_b128 v[148:151], v147 offset:1024
	ds_read_b128 v[152:155], v147 offset:2048
	ds_read_b128 v[156:159], v147 offset:3072
	v_add_u32_e32 v147, s15, v142
	ds_read_b128 v[160:163], v147
	ds_read_b128 v[164:167], v147 offset:1024
	ds_read_b128 v[168:171], v147 offset:2048
	ds_read_b128 v[172:175], v147 offset:3072
	s_mov_b32 m0, s24
	v_lshl_add_u64 v[220:221], v[218:219], 0, s[92:93]
	ds_read_b128 v[176:179], v146 offset:32768
	ds_read_b128 v[180:183], v146 offset:33792
	ds_read_b128 v[194:197], v146 offset:34816
	ds_read_b128 v[198:201], v146 offset:35840
	ds_read_b128 v[202:205], v146 offset:36864
	ds_read_b128 v[206:209], v146 offset:37888
	ds_read_b128 v[210:213], v146 offset:38912
	ds_read_b128 v[214:217], v146 offset:39936
	global_load_lds_dwordx4 v[220:221], off
	v_lshl_add_u64 v[220:221], v[218:219], 0, s[52:53]
	s_mov_b32 m0, s25
	s_nop 0
	global_load_lds_dwordx4 v[220:221], off
	s_waitcnt vmcnt(8)
	s_waitcnt lgkmcnt(0)
	s_barrier
	s_setprio 1
	s_waitcnt lgkmcnt(0)
	v_mfma_f32_16x16x32_bf16 v[124:127], v[134:137], v[176:179], v[124:127]
	v_mfma_f32_16x16x32_bf16 v[116:119], v[152:155], v[176:179], v[116:119]
	v_mfma_f32_16x16x32_bf16 v[108:111], v[134:137], v[194:197], v[108:111]
	v_mfma_f32_16x16x32_bf16 v[100:103], v[152:155], v[194:197], v[100:103]
	v_mfma_f32_16x16x32_bf16 v[92:95], v[134:137], v[202:205], v[92:95]
	v_mfma_f32_16x16x32_bf16 v[84:87], v[152:155], v[202:205], v[84:87]
	v_mfma_f32_16x16x32_bf16 v[76:79], v[134:137], v[210:213], v[76:79]
	v_mfma_f32_16x16x32_bf16 v[68:71], v[152:155], v[210:213], v[68:71]
	v_mfma_f32_16x16x32_bf16 v[124:127], v[148:151], v[180:183], v[124:127]
	v_mfma_f32_16x16x32_bf16 v[116:119], v[156:159], v[180:183], v[116:119]
	v_mfma_f32_16x16x32_bf16 v[108:111], v[148:151], v[198:201], v[108:111]
	v_mfma_f32_16x16x32_bf16 v[100:103], v[156:159], v[198:201], v[100:103]
	v_mfma_f32_16x16x32_bf16 v[92:95], v[148:151], v[206:209], v[92:95]
	v_mfma_f32_16x16x32_bf16 v[84:87], v[156:159], v[206:209], v[84:87]
	v_mfma_f32_16x16x32_bf16 v[76:79], v[148:151], v[214:217], v[76:79]
	v_mfma_f32_16x16x32_bf16 v[68:71], v[156:159], v[214:217], v[68:71]
	s_setprio 0
	s_setprio 1
	v_mfma_f32_16x16x32_bf16 v[120:123], v[160:163], v[176:179], v[120:123]
	v_mfma_f32_16x16x32_bf16 v[112:115], v[168:171], v[176:179], v[112:115]
	v_mfma_f32_16x16x32_bf16 v[104:107], v[160:163], v[194:197], v[104:107]
	v_mfma_f32_16x16x32_bf16 v[96:99], v[168:171], v[194:197], v[96:99]
	v_mfma_f32_16x16x32_bf16 v[88:91], v[160:163], v[202:205], v[88:91]
	v_mfma_f32_16x16x32_bf16 v[80:83], v[168:171], v[202:205], v[80:83]
	v_mfma_f32_16x16x32_bf16 v[72:75], v[160:163], v[210:213], v[72:75]
	v_mfma_f32_16x16x32_bf16 v[64:67], v[168:171], v[210:213], v[64:67]
	v_mfma_f32_16x16x32_bf16 v[120:123], v[164:167], v[180:183], v[120:123]
	v_mfma_f32_16x16x32_bf16 v[112:115], v[172:175], v[180:183], v[112:115]
	v_mfma_f32_16x16x32_bf16 v[104:107], v[164:167], v[198:201], v[104:107]
	v_mfma_f32_16x16x32_bf16 v[96:99], v[172:175], v[198:201], v[96:99]
	v_mfma_f32_16x16x32_bf16 v[88:91], v[164:167], v[206:209], v[88:91]
	v_mfma_f32_16x16x32_bf16 v[80:83], v[172:175], v[206:209], v[80:83]
	v_mfma_f32_16x16x32_bf16 v[72:75], v[164:167], v[214:217], v[72:75]
	v_mfma_f32_16x16x32_bf16 v[64:67], v[172:175], v[214:217], v[64:67]
	s_setprio 0
	s_barrier
	s_add_i32 s14, s14, s6
	v_lshl_add_u64 v[220:221], v[138:139], 0, s[56:57]
	s_mov_b32 m0, s14
	ds_read_b128 v[176:179], v146 offset:49152
	ds_read_b128 v[180:183], v146 offset:50176
	ds_read_b128 v[194:197], v146 offset:51200
	ds_read_b128 v[198:201], v146 offset:52224
	ds_read_b128 v[202:205], v146 offset:53248
	ds_read_b128 v[206:209], v146 offset:54272
	ds_read_b128 v[210:213], v146 offset:55296
	ds_read_b128 v[214:217], v146 offset:56320
	global_load_lds_dwordx4 v[220:221], off
	v_lshl_add_u64 v[220:221], v[138:139], 0, s[96:97]
	s_add_i32 m0, s14, 0x2000
	s_add_i32 s14, s15, s6
	global_load_lds_dwordx4 v[220:221], off
	v_lshl_add_u64 v[220:221], v[138:139], 0, s[88:89]
	s_mov_b32 m0, s14
	v_lshl_add_u64 v[138:139], v[138:139], 0, s[68:69]
	global_load_lds_dwordx4 v[220:221], off
	s_add_i32 m0, s14, 0x2000
	s_nop 0
	global_load_lds_dwordx4 v[138:139], off
	v_lshl_add_u64 v[138:139], v[218:219], 0, s[56:57]
	s_mov_b32 m0, s26
	s_nop 0
	global_load_lds_dwordx4 v[138:139], off
	v_lshl_add_u64 v[138:139], v[218:219], 0, s[96:97]
	s_mov_b32 m0, s27
	s_nop 0
	global_load_lds_dwordx4 v[138:139], off
	s_waitcnt vmcnt(8)
	s_waitcnt lgkmcnt(0)
	s_barrier
	s_setprio 1
	s_waitcnt lgkmcnt(0)
	v_mfma_f32_16x16x32_bf16 v[60:63], v[134:137], v[176:179], v[60:63]
	v_mfma_f32_16x16x32_bf16 v[52:55], v[152:155], v[176:179], v[52:55]
	v_mfma_f32_16x16x32_bf16 v[44:47], v[134:137], v[194:197], v[44:47]
	v_mfma_f32_16x16x32_bf16 v[36:39], v[152:155], v[194:197], v[36:39]
	v_mfma_f32_16x16x32_bf16 v[28:31], v[134:137], v[202:205], v[28:31]
	v_mfma_f32_16x16x32_bf16 v[20:23], v[152:155], v[202:205], v[20:23]
	v_mfma_f32_16x16x32_bf16 v[12:15], v[134:137], v[210:213], v[12:15]
	v_mfma_f32_16x16x32_bf16 v[4:7], v[152:155], v[210:213], v[4:7]
	v_mfma_f32_16x16x32_bf16 v[60:63], v[148:151], v[180:183], v[60:63]
	v_mfma_f32_16x16x32_bf16 v[52:55], v[156:159], v[180:183], v[52:55]
	v_mfma_f32_16x16x32_bf16 v[44:47], v[148:151], v[198:201], v[44:47]
	v_mfma_f32_16x16x32_bf16 v[36:39], v[156:159], v[198:201], v[36:39]
	v_mfma_f32_16x16x32_bf16 v[28:31], v[148:151], v[206:209], v[28:31]
	v_mfma_f32_16x16x32_bf16 v[20:23], v[156:159], v[206:209], v[20:23]
	v_mfma_f32_16x16x32_bf16 v[12:15], v[148:151], v[214:217], v[12:15]
	v_mfma_f32_16x16x32_bf16 v[4:7], v[156:159], v[214:217], v[4:7]
	s_setprio 0
	s_setprio 1
	v_mfma_f32_16x16x32_bf16 v[56:59], v[160:163], v[176:179], v[56:59]
	v_mfma_f32_16x16x32_bf16 v[48:51], v[168:171], v[176:179], v[48:51]
	v_mfma_f32_16x16x32_bf16 v[40:43], v[160:163], v[194:197], v[40:43]
	v_mfma_f32_16x16x32_bf16 v[32:35], v[168:171], v[194:197], v[32:35]
	v_mfma_f32_16x16x32_bf16 v[24:27], v[160:163], v[202:205], v[24:27]
	v_mfma_f32_16x16x32_bf16 v[16:19], v[168:171], v[202:205], v[16:19]
	v_mfma_f32_16x16x32_bf16 v[8:11], v[160:163], v[210:213], v[8:11]
	v_mfma_f32_16x16x32_bf16 v[0:3], v[168:171], v[210:213], v[0:3]
	v_mfma_f32_16x16x32_bf16 v[56:59], v[164:167], v[180:183], v[56:59]
	v_mfma_f32_16x16x32_bf16 v[48:51], v[172:175], v[180:183], v[48:51]
	v_mfma_f32_16x16x32_bf16 v[40:43], v[164:167], v[198:201], v[40:43]
	v_mfma_f32_16x16x32_bf16 v[32:35], v[172:175], v[198:201], v[32:35]
	v_mfma_f32_16x16x32_bf16 v[24:27], v[164:167], v[206:209], v[24:27]
	v_mfma_f32_16x16x32_bf16 v[16:19], v[172:175], v[206:209], v[16:19]
	v_mfma_f32_16x16x32_bf16 v[8:11], v[164:167], v[214:217], v[8:11]
	v_mfma_f32_16x16x32_bf16 v[0:3], v[172:175], v[214:217], v[0:3]
	s_setprio 0
	s_barrier
	s_add_i32 s51, s51, 2
	s_add_u32 s48, s48, 0x100
	s_addc_u32 s49, s49, 0
	s_add_u32 s16, s16, 0x100
	s_addc_u32 s17, s17, 0
	s_cmp_gt_u32 s51, 13

.LBB0_480:
	s_ashr_i32 s41, s40, 31
	s_lshl_b64 s[42:43], s[40:41], 19
	s_add_u32 s42, s64, s42
	s_addc_u32 s43, s65, s43
	s_and_b64 s[44:45], s[38:39], exec
	s_cselect_b32 s31, s43, s17
	s_cselect_b32 s41, s42, s16
	s_ashr_i32 s13, s12, 31
	s_lshl_b64 s[44:45], s[12:13], 19
	s_add_u32 s44, s22, s44
	s_addc_u32 s45, s23, s45
	s_and_b64 s[46:47], s[38:39], exec
	s_cselect_b32 s13, s45, s15
	s_cselect_b32 s48, s44, s14
	s_add_u32 s46, s16, 0x40080
	s_addc_u32 s47, s17, 0
	s_add_u32 s16, s14, 0x100
	s_addc_u32 s17, s15, 0
	s_mov_b32 s49, -2
	s_add_u32 s14, s46, 0xfffc0080
	s_addc_u32 s15, s47, -1
	s_add_i32 s60, 0, 0x10000
	s_cmp_eq_u32 s49, 12
	s_cselect_b32 s15, s31, s15
	s_cselect_b32 s14, s41, s14
	v_add_u32_e32 v135, s60, v143
	s_cselect_b32 s51, s13, s17
	s_cselect_b32 s50, s48, s16
	s_add_i32 s61, 0, 0x14000
	ds_read_b128 v[136:139], v135
	ds_read_b128 v[148:151], v135 offset:1024
	ds_read_b128 v[152:155], v135 offset:2048
	ds_read_b128 v[156:159], v135 offset:3072
	v_add_u32_e32 v135, s61, v143
	ds_read_b128 v[160:163], v135
	ds_read_b128 v[164:167], v135 offset:1024
	ds_read_b128 v[168:171], v135 offset:2048
	ds_read_b128 v[172:175], v135 offset:3072
	v_lshl_add_u64 v[140:141], s[46:47], 0, v[184:185]
	s_add_i32 m0, s19, 0xc000
	ds_read_b128 v[176:179], v147
	ds_read_b128 v[180:183], v147 offset:1024
	ds_read_b128 v[194:197], v147 offset:2048
	ds_read_b128 v[198:201], v147 offset:3072
	ds_read_b128 v[202:205], v147 offset:4096
	ds_read_b128 v[206:209], v147 offset:5120
	ds_read_b128 v[210:213], v147 offset:6144
	ds_read_b128 v[214:217], v147 offset:7168
	global_load_lds_dwordx4 v[140:141], off
	v_lshl_add_u64 v[140:141], v[140:141], 0, s[34:35]
	s_add_i32 m0, s19, 0xe000
	s_nop 0
	global_load_lds_dwordx4 v[140:141], off
	s_waitcnt vmcnt(8)
	s_waitcnt lgkmcnt(0)
	s_barrier
	s_setprio 1
	s_waitcnt lgkmcnt(0)
	v_mfma_f32_16x16x32_bf16 v[124:127], v[136:139], v[176:179], 0
	v_mfma_f32_16x16x32_bf16 v[116:119], v[152:155], v[176:179], 0
	v_mfma_f32_16x16x32_bf16 v[108:111], v[136:139], v[194:197], 0
	v_mfma_f32_16x16x32_bf16 v[100:103], v[152:155], v[194:197], 0
	v_mfma_f32_16x16x32_bf16 v[92:95], v[136:139], v[202:205], 0
	v_mfma_f32_16x16x32_bf16 v[84:87], v[152:155], v[202:205], 0
	v_mfma_f32_16x16x32_bf16 v[76:79], v[136:139], v[210:213], 0
	v_mfma_f32_16x16x32_bf16 v[68:71], v[152:155], v[210:213], 0
	v_mfma_f32_16x16x32_bf16 v[124:127], v[148:151], v[180:183], v[124:127]
	v_mfma_f32_16x16x32_bf16 v[116:119], v[156:159], v[180:183], v[116:119]
	v_mfma_f32_16x16x32_bf16 v[108:111], v[148:151], v[198:201], v[108:111]
	v_mfma_f32_16x16x32_bf16 v[100:103], v[156:159], v[198:201], v[100:103]
	v_mfma_f32_16x16x32_bf16 v[92:95], v[148:151], v[206:209], v[92:95]
	v_mfma_f32_16x16x32_bf16 v[84:87], v[156:159], v[206:209], v[84:87]
	v_mfma_f32_16x16x32_bf16 v[76:79], v[148:151], v[214:217], v[76:79]
	v_mfma_f32_16x16x32_bf16 v[68:71], v[156:159], v[214:217], v[68:71]
	s_setprio 0
	s_setprio 1
	v_mfma_f32_16x16x32_bf16 v[120:123], v[160:163], v[176:179], 0
	v_mfma_f32_16x16x32_bf16 v[112:115], v[168:171], v[176:179], 0
	v_mfma_f32_16x16x32_bf16 v[104:107], v[160:163], v[194:197], 0
	v_mfma_f32_16x16x32_bf16 v[96:99], v[168:171], v[194:197], 0
	v_mfma_f32_16x16x32_bf16 v[88:91], v[160:163], v[202:205], 0
	v_mfma_f32_16x16x32_bf16 v[80:83], v[168:171], v[202:205], 0
	v_mfma_f32_16x16x32_bf16 v[72:75], v[160:163], v[210:213], 0
	v_mfma_f32_16x16x32_bf16 v[64:67], v[168:171], v[210:213], 0
	v_mfma_f32_16x16x32_bf16 v[120:123], v[164:167], v[180:183], v[120:123]
	v_mfma_f32_16x16x32_bf16 v[112:115], v[172:175], v[180:183], v[112:115]
	v_mfma_f32_16x16x32_bf16 v[104:107], v[164:167], v[198:201], v[104:107]
	v_mfma_f32_16x16x32_bf16 v[96:99], v[172:175], v[198:201], v[96:99]
	v_mfma_f32_16x16x32_bf16 v[88:91], v[164:167], v[206:209], v[88:91]
	v_mfma_f32_16x16x32_bf16 v[80:83], v[172:175], v[206:209], v[80:83]
	v_mfma_f32_16x16x32_bf16 v[72:75], v[164:167], v[214:217], v[72:75]
	v_mfma_f32_16x16x32_bf16 v[64:67], v[172:175], v[214:217], v[64:67]
	s_setprio 0
	s_barrier
	v_lshl_add_u64 v[140:141], s[50:51], 0, v[128:129]
	s_add_i32 s50, s60, s6
	s_mov_b32 m0, s50
	ds_read_b128 v[176:179], v147 offset:16384
	ds_read_b128 v[180:183], v147 offset:17408
	ds_read_b128 v[194:197], v147 offset:18432
	ds_read_b128 v[198:201], v147 offset:19456
	ds_read_b128 v[202:205], v147 offset:20480
	ds_read_b128 v[206:209], v147 offset:21504
	ds_read_b128 v[210:213], v147 offset:22528
	ds_read_b128 v[214:217], v147 offset:23552
	global_load_lds_dwordx4 v[140:141], off
	v_lshl_add_u64 v[218:219], v[140:141], 0, s[34:35]
	s_add_i32 m0, s50, 0x2000
	s_add_i32 s50, s61, s6
	global_load_lds_dwordx4 v[218:219], off
	v_lshl_add_u64 v[218:219], v[140:141], 0, s[92:93]
	s_mov_b32 m0, s50
	s_nop 0
	global_load_lds_dwordx4 v[218:219], off
	v_lshl_add_u64 v[218:219], v[140:141], 0, s[52:53]
	s_add_i32 m0, s50, 0x2000
	s_nop 0
	global_load_lds_dwordx4 v[218:219], off
	v_lshl_add_u64 v[218:219], s[14:15], 0, v[130:131]
	s_mov_b32 m0, s19
	v_lshl_add_u64 v[220:221], v[218:219], 0, s[34:35]
	global_load_lds_dwordx4 v[218:219], off
	s_mov_b32 m0, s20
	s_nop 0
	global_load_lds_dwordx4 v[220:221], off
	s_waitcnt vmcnt(8)
	s_waitcnt lgkmcnt(0)
	s_barrier
	s_setprio 1
	s_waitcnt lgkmcnt(0)
	v_mfma_f32_16x16x32_bf16 v[60:63], v[136:139], v[176:179], 0
	v_mfma_f32_16x16x32_bf16 v[52:55], v[152:155], v[176:179], 0
	v_mfma_f32_16x16x32_bf16 v[44:47], v[136:139], v[194:197], 0
	v_mfma_f32_16x16x32_bf16 v[36:39], v[152:155], v[194:197], 0
	v_mfma_f32_16x16x32_bf16 v[28:31], v[136:139], v[202:205], 0
	v_mfma_f32_16x16x32_bf16 v[20:23], v[152:155], v[202:205], 0
	v_mfma_f32_16x16x32_bf16 v[12:15], v[136:139], v[210:213], 0
	v_mfma_f32_16x16x32_bf16 v[4:7], v[152:155], v[210:213], 0
	v_mfma_f32_16x16x32_bf16 v[60:63], v[148:151], v[180:183], v[60:63]
	v_mfma_f32_16x16x32_bf16 v[52:55], v[156:159], v[180:183], v[52:55]
	v_mfma_f32_16x16x32_bf16 v[44:47], v[148:151], v[198:201], v[44:47]
	v_mfma_f32_16x16x32_bf16 v[36:39], v[156:159], v[198:201], v[36:39]
	v_mfma_f32_16x16x32_bf16 v[28:31], v[148:151], v[206:209], v[28:31]
	v_mfma_f32_16x16x32_bf16 v[20:23], v[156:159], v[206:209], v[20:23]
	v_mfma_f32_16x16x32_bf16 v[12:15], v[148:151], v[214:217], v[12:15]
	v_mfma_f32_16x16x32_bf16 v[4:7], v[156:159], v[214:217], v[4:7]
	s_setprio 0
	s_setprio 1
	v_mfma_f32_16x16x32_bf16 v[56:59], v[160:163], v[176:179], 0
	v_mfma_f32_16x16x32_bf16 v[48:51], v[168:171], v[176:179], 0
	v_mfma_f32_16x16x32_bf16 v[40:43], v[160:163], v[194:197], 0
	v_mfma_f32_16x16x32_bf16 v[32:35], v[168:171], v[194:197], 0
	v_mfma_f32_16x16x32_bf16 v[24:27], v[160:163], v[202:205], 0
	v_mfma_f32_16x16x32_bf16 v[16:19], v[168:171], v[202:205], 0
	v_mfma_f32_16x16x32_bf16 v[8:11], v[160:163], v[210:213], 0
	v_mfma_f32_16x16x32_bf16 v[0:3], v[168:171], v[210:213], 0
	v_mfma_f32_16x16x32_bf16 v[56:59], v[164:167], v[180:183], v[56:59]
	v_mfma_f32_16x16x32_bf16 v[48:51], v[172:175], v[180:183], v[48:51]
	v_mfma_f32_16x16x32_bf16 v[40:43], v[164:167], v[198:201], v[40:43]
	v_mfma_f32_16x16x32_bf16 v[32:35], v[172:175], v[198:201], v[32:35]
	v_mfma_f32_16x16x32_bf16 v[24:27], v[164:167], v[206:209], v[24:27]
	v_mfma_f32_16x16x32_bf16 v[16:19], v[172:175], v[206:209], v[16:19]
	v_mfma_f32_16x16x32_bf16 v[8:11], v[164:167], v[214:217], v[8:11]
	v_mfma_f32_16x16x32_bf16 v[0:3], v[172:175], v[214:217], v[0:3]
	s_setprio 0
	s_barrier
	s_add_i32 s14, 0, 0x18000
	v_add_u32_e32 v135, s14, v143
	s_add_i32 s15, 0, 0x1c000
	ds_read_b128 v[136:139], v135
	ds_read_b128 v[148:151], v135 offset:1024
	ds_read_b128 v[152:155], v135 offset:2048
	ds_read_b128 v[156:159], v135 offset:3072
	v_add_u32_e32 v135, s15, v143
	ds_read_b128 v[160:163], v135
	ds_read_b128 v[164:167], v135 offset:1024
	ds_read_b128 v[168:171], v135 offset:2048
	ds_read_b128 v[172:175], v135 offset:3072
	s_mov_b32 m0, s24
	v_lshl_add_u64 v[220:221], v[218:219], 0, s[92:93]
	ds_read_b128 v[176:179], v147 offset:32768
	ds_read_b128 v[180:183], v147 offset:33792
	ds_read_b128 v[194:197], v147 offset:34816
	ds_read_b128 v[198:201], v147 offset:35840
	ds_read_b128 v[202:205], v147 offset:36864
	ds_read_b128 v[206:209], v147 offset:37888
	ds_read_b128 v[210:213], v147 offset:38912
	ds_read_b128 v[214:217], v147 offset:39936
	global_load_lds_dwordx4 v[220:221], off
	v_lshl_add_u64 v[220:221], v[218:219], 0, s[52:53]
	s_mov_b32 m0, s25
	s_nop 0
	global_load_lds_dwordx4 v[220:221], off
	s_waitcnt vmcnt(8)
	s_waitcnt lgkmcnt(0)
	s_barrier
	s_setprio 1
	s_waitcnt lgkmcnt(0)
	v_mfma_f32_16x16x32_bf16 v[124:127], v[136:139], v[176:179], v[124:127]
	v_mfma_f32_16x16x32_bf16 v[116:119], v[152:155], v[176:179], v[116:119]
	v_mfma_f32_16x16x32_bf16 v[108:111], v[136:139], v[194:197], v[108:111]
	v_mfma_f32_16x16x32_bf16 v[100:103], v[152:155], v[194:197], v[100:103]
	v_mfma_f32_16x16x32_bf16 v[92:95], v[136:139], v[202:205], v[92:95]
	v_mfma_f32_16x16x32_bf16 v[84:87], v[152:155], v[202:205], v[84:87]
	v_mfma_f32_16x16x32_bf16 v[76:79], v[136:139], v[210:213], v[76:79]
	v_mfma_f32_16x16x32_bf16 v[68:71], v[152:155], v[210:213], v[68:71]
	v_mfma_f32_16x16x32_bf16 v[124:127], v[148:151], v[180:183], v[124:127]
	v_mfma_f32_16x16x32_bf16 v[116:119], v[156:159], v[180:183], v[116:119]
	v_mfma_f32_16x16x32_bf16 v[108:111], v[148:151], v[198:201], v[108:111]
	v_mfma_f32_16x16x32_bf16 v[100:103], v[156:159], v[198:201], v[100:103]
	v_mfma_f32_16x16x32_bf16 v[92:95], v[148:151], v[206:209], v[92:95]
	v_mfma_f32_16x16x32_bf16 v[84:87], v[156:159], v[206:209], v[84:87]
	v_mfma_f32_16x16x32_bf16 v[76:79], v[148:151], v[214:217], v[76:79]
	v_mfma_f32_16x16x32_bf16 v[68:71], v[156:159], v[214:217], v[68:71]
	s_setprio 0
	s_setprio 1
	v_mfma_f32_16x16x32_bf16 v[120:123], v[160:163], v[176:179], v[120:123]
	v_mfma_f32_16x16x32_bf16 v[112:115], v[168:171], v[176:179], v[112:115]
	v_mfma_f32_16x16x32_bf16 v[104:107], v[160:163], v[194:197], v[104:107]
	v_mfma_f32_16x16x32_bf16 v[96:99], v[168:171], v[194:197], v[96:99]
	v_mfma_f32_16x16x32_bf16 v[88:91], v[160:163], v[202:205], v[88:91]
	v_mfma_f32_16x16x32_bf16 v[80:83], v[168:171], v[202:205], v[80:83]
	v_mfma_f32_16x16x32_bf16 v[72:75], v[160:163], v[210:213], v[72:75]
	v_mfma_f32_16x16x32_bf16 v[64:67], v[168:171], v[210:213], v[64:67]
	v_mfma_f32_16x16x32_bf16 v[120:123], v[164:167], v[180:183], v[120:123]
	v_mfma_f32_16x16x32_bf16 v[112:115], v[172:175], v[180:183], v[112:115]
	v_mfma_f32_16x16x32_bf16 v[104:107], v[164:167], v[198:201], v[104:107]
	v_mfma_f32_16x16x32_bf16 v[96:99], v[172:175], v[198:201], v[96:99]
	v_mfma_f32_16x16x32_bf16 v[88:91], v[164:167], v[206:209], v[88:91]
	v_mfma_f32_16x16x32_bf16 v[80:83], v[172:175], v[206:209], v[80:83]
	v_mfma_f32_16x16x32_bf16 v[72:75], v[164:167], v[214:217], v[72:75]
	v_mfma_f32_16x16x32_bf16 v[64:67], v[172:175], v[214:217], v[64:67]
	s_setprio 0
	s_barrier
	s_add_i32 s14, s14, s6
	v_lshl_add_u64 v[220:221], v[140:141], 0, s[56:57]
	s_mov_b32 m0, s14
	ds_read_b128 v[176:179], v147 offset:49152
	ds_read_b128 v[180:183], v147 offset:50176
	ds_read_b128 v[194:197], v147 offset:51200
	ds_read_b128 v[198:201], v147 offset:52224
	ds_read_b128 v[202:205], v147 offset:53248
	ds_read_b128 v[206:209], v147 offset:54272
	ds_read_b128 v[210:213], v147 offset:55296
	ds_read_b128 v[214:217], v147 offset:56320
	global_load_lds_dwordx4 v[220:221], off
	v_lshl_add_u64 v[220:221], v[140:141], 0, s[96:97]
	s_add_i32 m0, s14, 0x2000
	s_add_i32 s14, s15, s6
	global_load_lds_dwordx4 v[220:221], off
	v_lshl_add_u64 v[220:221], v[140:141], 0, s[88:89]
	s_mov_b32 m0, s14
	v_lshl_add_u64 v[140:141], v[140:141], 0, s[68:69]
	global_load_lds_dwordx4 v[220:221], off
	s_add_i32 m0, s14, 0x2000
	s_nop 0
	global_load_lds_dwordx4 v[140:141], off
	v_lshl_add_u64 v[140:141], v[218:219], 0, s[56:57]
	s_mov_b32 m0, s26
	s_nop 0
	global_load_lds_dwordx4 v[140:141], off
	v_lshl_add_u64 v[140:141], v[218:219], 0, s[96:97]
	s_mov_b32 m0, s27
	s_nop 0
	global_load_lds_dwordx4 v[140:141], off
	s_waitcnt vmcnt(8)
	s_waitcnt lgkmcnt(0)
	s_barrier
	s_setprio 1
	s_waitcnt lgkmcnt(0)
	v_mfma_f32_16x16x32_bf16 v[60:63], v[136:139], v[176:179], v[60:63]
	v_mfma_f32_16x16x32_bf16 v[52:55], v[152:155], v[176:179], v[52:55]
	v_mfma_f32_16x16x32_bf16 v[44:47], v[136:139], v[194:197], v[44:47]
	v_mfma_f32_16x16x32_bf16 v[36:39], v[152:155], v[194:197], v[36:39]
	v_mfma_f32_16x16x32_bf16 v[28:31], v[136:139], v[202:205], v[28:31]
	v_mfma_f32_16x16x32_bf16 v[20:23], v[152:155], v[202:205], v[20:23]
	v_mfma_f32_16x16x32_bf16 v[12:15], v[136:139], v[210:213], v[12:15]
	v_mfma_f32_16x16x32_bf16 v[4:7], v[152:155], v[210:213], v[4:7]
	v_mfma_f32_16x16x32_bf16 v[60:63], v[148:151], v[180:183], v[60:63]
	v_mfma_f32_16x16x32_bf16 v[52:55], v[156:159], v[180:183], v[52:55]
	v_mfma_f32_16x16x32_bf16 v[44:47], v[148:151], v[198:201], v[44:47]
	v_mfma_f32_16x16x32_bf16 v[36:39], v[156:159], v[198:201], v[36:39]
	v_mfma_f32_16x16x32_bf16 v[28:31], v[148:151], v[206:209], v[28:31]
	v_mfma_f32_16x16x32_bf16 v[20:23], v[156:159], v[206:209], v[20:23]
	v_mfma_f32_16x16x32_bf16 v[12:15], v[148:151], v[214:217], v[12:15]
	v_mfma_f32_16x16x32_bf16 v[4:7], v[156:159], v[214:217], v[4:7]
	s_setprio 0
	s_setprio 1
	v_mfma_f32_16x16x32_bf16 v[56:59], v[160:163], v[176:179], v[56:59]
	v_mfma_f32_16x16x32_bf16 v[48:51], v[168:171], v[176:179], v[48:51]
	v_mfma_f32_16x16x32_bf16 v[40:43], v[160:163], v[194:197], v[40:43]
	v_mfma_f32_16x16x32_bf16 v[32:35], v[168:171], v[194:197], v[32:35]
	v_mfma_f32_16x16x32_bf16 v[24:27], v[160:163], v[202:205], v[24:27]
	v_mfma_f32_16x16x32_bf16 v[16:19], v[168:171], v[202:205], v[16:19]
	v_mfma_f32_16x16x32_bf16 v[8:11], v[160:163], v[210:213], v[8:11]
	v_mfma_f32_16x16x32_bf16 v[0:3], v[168:171], v[210:213], v[0:3]
	v_mfma_f32_16x16x32_bf16 v[56:59], v[164:167], v[180:183], v[56:59]
	v_mfma_f32_16x16x32_bf16 v[48:51], v[172:175], v[180:183], v[48:51]
	v_mfma_f32_16x16x32_bf16 v[40:43], v[164:167], v[198:201], v[40:43]
	v_mfma_f32_16x16x32_bf16 v[32:35], v[172:175], v[198:201], v[32:35]
	v_mfma_f32_16x16x32_bf16 v[24:27], v[164:167], v[206:209], v[24:27]
	v_mfma_f32_16x16x32_bf16 v[16:19], v[172:175], v[206:209], v[16:19]
	v_mfma_f32_16x16x32_bf16 v[8:11], v[164:167], v[214:217], v[8:11]
	v_mfma_f32_16x16x32_bf16 v[0:3], v[172:175], v[214:217], v[0:3]
	s_setprio 0
	s_barrier
	s_add_i32 s49, s49, 2
	s_add_u32 s46, s46, 0x100
	s_addc_u32 s47, s47, 0
	s_add_u32 s16, s16, 0x100
	s_addc_u32 s17, s17, 0
	s_cmp_gt_u32 s49, 13

.LBB0_502:
	s_ashr_i32 s13, s12, 31
	s_lshl_b64 s[42:43], s[12:13], 18
	s_add_u32 s42, s54, s42
	s_addc_u32 s43, s55, s43
	s_and_b64 s[44:45], s[40:41], exec
	s_cselect_b32 s13, s43, s17
	s_cselect_b32 s31, s42, s16
	s_ashr_i32 s11, s10, 31
	s_lshl_b64 s[44:45], s[10:11], 18
	s_add_u32 s44, s22, s44
	s_addc_u32 s45, s23, s45
	s_and_b64 s[46:47], s[40:41], exec
	s_cselect_b32 s11, s45, s15
	s_cselect_b32 s48, s44, s14
	s_add_u32 s46, s16, 0x20080
	s_addc_u32 s47, s17, 0
	s_add_u32 s49, s14, 0x100
	s_addc_u32 s50, s15, 0
	s_mov_b32 s51, -2
	s_add_u32 s14, s46, 0xfffe0080
	s_addc_u32 s15, s47, -1
	s_add_i32 s60, 0, 0x10000
	s_cmp_eq_u32 s51, 4
	s_cselect_b32 s15, s13, s15
	s_cselect_b32 s14, s31, s14
	s_cselect_b32 s17, s11, s50
	s_cselect_b32 s16, s48, s49
	s_add_i32 s61, 0, 0x14000
	v_add_u32_e32 v0, s60, v172
	v_add_u32_e32 v4, s61, v172
	ds_read_b128 v[24:27], v0
	ds_read_b128 v[28:31], v0 offset:1024
	ds_read_b128 v[16:19], v0 offset:2048
	ds_read_b128 v[20:23], v0 offset:3072
	ds_read_b128 v[8:11], v4
	ds_read_b128 v[12:15], v4 offset:1024
	ds_read_b128 v[0:3], v4 offset:2048
	ds_read_b128 v[4:7], v4 offset:3072
	v_lshl_add_u64 v[166:167], s[46:47], 0, v[164:165]
	s_add_i32 m0, s19, 0xc000
	ds_read_b128 v[194:197], v176
	ds_read_b128 v[198:201], v176 offset:1024
	ds_read_b128 v[202:205], v176 offset:2048
	ds_read_b128 v[206:209], v176 offset:3072
	ds_read_b128 v[210:213], v176 offset:4096
	ds_read_b128 v[214:217], v176 offset:5120
	ds_read_b128 v[218:221], v176 offset:6144
	ds_read_b128 v[222:225], v176 offset:7168
	global_load_lds_dwordx4 v[166:167], off
	v_lshl_add_u64 v[166:167], v[166:167], 0, s[94:95]
	s_add_i32 m0, s19, 0xe000
	s_nop 0
	global_load_lds_dwordx4 v[166:167], off
	s_waitcnt vmcnt(8)
	s_waitcnt lgkmcnt(0)
	s_barrier
	s_setprio 1
	s_waitcnt lgkmcnt(0)
	v_mfma_scale_f32_16x16x128_f8f6f4 v[156:159], v[24:31], v[194:201], 0, v240, v240 op_sel_hi:[0,0,0]
	v_mfma_scale_f32_16x16x128_f8f6f4 v[148:151], v[16:23], v[194:201], 0, v240, v240 op_sel_hi:[0,0,0]
	v_mfma_scale_f32_16x16x128_f8f6f4 v[140:143], v[24:31], v[202:209], 0, v240, v240 op_sel_hi:[0,0,0]
	v_mfma_scale_f32_16x16x128_f8f6f4 v[132:135], v[16:23], v[202:209], 0, v240, v240 op_sel_hi:[0,0,0]
	v_mfma_scale_f32_16x16x128_f8f6f4 v[124:127], v[24:31], v[210:217], 0, v240, v240 op_sel_hi:[0,0,0]
	v_mfma_scale_f32_16x16x128_f8f6f4 v[116:119], v[16:23], v[210:217], 0, v240, v240 op_sel_hi:[0,0,0]
	v_mfma_scale_f32_16x16x128_f8f6f4 v[108:111], v[24:31], v[218:225], 0, v240, v240 op_sel_hi:[0,0,0]
	v_mfma_scale_f32_16x16x128_f8f6f4 v[100:103], v[16:23], v[218:225], 0, v240, v240 op_sel_hi:[0,0,0]
	s_setprio 0
	s_setprio 1
	v_mfma_scale_f32_16x16x128_f8f6f4 v[152:155], v[8:15], v[194:201], 0, v240, v240 op_sel_hi:[0,0,0]
	v_mfma_scale_f32_16x16x128_f8f6f4 v[144:147], v[0:7], v[194:201], 0, v240, v240 op_sel_hi:[0,0,0]
	v_mfma_scale_f32_16x16x128_f8f6f4 v[136:139], v[8:15], v[202:209], 0, v240, v240 op_sel_hi:[0,0,0]
	v_mfma_scale_f32_16x16x128_f8f6f4 v[128:131], v[0:7], v[202:209], 0, v240, v240 op_sel_hi:[0,0,0]
	v_mfma_scale_f32_16x16x128_f8f6f4 v[120:123], v[8:15], v[210:217], 0, v240, v240 op_sel_hi:[0,0,0]
	v_mfma_scale_f32_16x16x128_f8f6f4 v[112:115], v[0:7], v[210:217], 0, v240, v240 op_sel_hi:[0,0,0]
	v_mfma_scale_f32_16x16x128_f8f6f4 v[104:107], v[8:15], v[218:225], 0, v240, v240 op_sel_hi:[0,0,0]
	v_mfma_scale_f32_16x16x128_f8f6f4 v[96:99], v[0:7], v[218:225], 0, v240, v240 op_sel_hi:[0,0,0]
	s_setprio 0
	s_barrier
	v_lshl_add_u64 v[166:167], s[16:17], 0, v[184:185]
	s_add_i32 s16, s60, s6
	s_mov_b32 m0, s16
	ds_read_b128 v[194:197], v176 offset:16384
	ds_read_b128 v[198:201], v176 offset:17408
	ds_read_b128 v[202:205], v176 offset:18432
	ds_read_b128 v[206:209], v176 offset:19456
	ds_read_b128 v[210:213], v176 offset:20480
	ds_read_b128 v[214:217], v176 offset:21504
	ds_read_b128 v[218:221], v176 offset:22528
	ds_read_b128 v[222:225], v176 offset:23552
	global_load_lds_dwordx4 v[166:167], off
	v_lshl_add_u64 v[168:169], v[166:167], 0, s[94:95]
	s_add_i32 m0, s16, 0x2000
	s_add_i32 s16, s61, s6
	global_load_lds_dwordx4 v[168:169], off
	v_lshl_add_u64 v[168:169], v[166:167], 0, s[34:35]
	s_mov_b32 m0, s16
	s_nop 0
	global_load_lds_dwordx4 v[168:169], off
	v_lshl_add_u64 v[168:169], v[166:167], 0, s[90:91]
	s_add_i32 m0, s16, 0x2000
	s_nop 0
	global_load_lds_dwordx4 v[168:169], off
	v_lshl_add_u64 v[168:169], s[14:15], 0, v[160:161]
	s_mov_b32 m0, s19
	v_lshl_add_u64 v[178:179], v[168:169], 0, s[94:95]
	global_load_lds_dwordx4 v[168:169], off
	s_mov_b32 m0, s20
	s_nop 0
	global_load_lds_dwordx4 v[178:179], off
	s_waitcnt vmcnt(8)
	s_waitcnt lgkmcnt(0)
	s_barrier
	s_setprio 1
	s_waitcnt lgkmcnt(0)
	v_mfma_scale_f32_16x16x128_f8f6f4 v[92:95], v[24:31], v[194:201], 0, v240, v240 op_sel_hi:[0,0,0]
	v_mfma_scale_f32_16x16x128_f8f6f4 v[84:87], v[16:23], v[194:201], 0, v240, v240 op_sel_hi:[0,0,0]
	v_mfma_scale_f32_16x16x128_f8f6f4 v[76:79], v[24:31], v[202:209], 0, v240, v240 op_sel_hi:[0,0,0]
	v_mfma_scale_f32_16x16x128_f8f6f4 v[68:71], v[16:23], v[202:209], 0, v240, v240 op_sel_hi:[0,0,0]
	v_mfma_scale_f32_16x16x128_f8f6f4 v[60:63], v[24:31], v[210:217], 0, v240, v240 op_sel_hi:[0,0,0]
	v_mfma_scale_f32_16x16x128_f8f6f4 v[52:55], v[16:23], v[210:217], 0, v240, v240 op_sel_hi:[0,0,0]
	v_mfma_scale_f32_16x16x128_f8f6f4 v[44:47], v[24:31], v[218:225], 0, v240, v240 op_sel_hi:[0,0,0]
	v_mfma_scale_f32_16x16x128_f8f6f4 v[36:39], v[16:23], v[218:225], 0, v240, v240 op_sel_hi:[0,0,0]
	s_setprio 0
	s_setprio 1
	v_mfma_scale_f32_16x16x128_f8f6f4 v[88:91], v[8:15], v[194:201], 0, v240, v240 op_sel_hi:[0,0,0]
	v_mfma_scale_f32_16x16x128_f8f6f4 v[80:83], v[0:7], v[194:201], 0, v240, v240 op_sel_hi:[0,0,0]
	v_mfma_scale_f32_16x16x128_f8f6f4 v[72:75], v[8:15], v[202:209], 0, v240, v240 op_sel_hi:[0,0,0]
	v_mfma_scale_f32_16x16x128_f8f6f4 v[64:67], v[0:7], v[202:209], 0, v240, v240 op_sel_hi:[0,0,0]
	v_mfma_scale_f32_16x16x128_f8f6f4 v[56:59], v[8:15], v[210:217], 0, v240, v240 op_sel_hi:[0,0,0]
	v_mfma_scale_f32_16x16x128_f8f6f4 v[48:51], v[0:7], v[210:217], 0, v240, v240 op_sel_hi:[0,0,0]
	v_mfma_scale_f32_16x16x128_f8f6f4 v[40:43], v[8:15], v[218:225], 0, v240, v240 op_sel_hi:[0,0,0]
	v_mfma_scale_f32_16x16x128_f8f6f4 v[32:35], v[0:7], v[218:225], 0, v240, v240 op_sel_hi:[0,0,0]
	s_setprio 0
	s_barrier
	s_add_i32 s14, 0, 0x18000
	s_add_i32 s15, 0, 0x1c000
	v_add_u32_e32 v12, s14, v172
	v_add_u32_e32 v28, s15, v172
	ds_read_b128 v[0:3], v12
	ds_read_b128 v[4:7], v12 offset:1024
	ds_read_b128 v[8:11], v12 offset:2048
	ds_read_b128 v[12:15], v12 offset:3072
	ds_read_b128 v[16:19], v28
	ds_read_b128 v[20:23], v28 offset:1024
	ds_read_b128 v[24:27], v28 offset:2048
	ds_read_b128 v[28:31], v28 offset:3072
	s_mov_b32 m0, s24
	v_lshl_add_u64 v[178:179], v[168:169], 0, s[34:35]
	ds_read_b128 v[194:197], v176 offset:32768
	ds_read_b128 v[198:201], v176 offset:33792
	ds_read_b128 v[202:205], v176 offset:34816
	ds_read_b128 v[206:209], v176 offset:35840
	ds_read_b128 v[210:213], v176 offset:36864
	ds_read_b128 v[214:217], v176 offset:37888
	ds_read_b128 v[218:221], v176 offset:38912
	ds_read_b128 v[222:225], v176 offset:39936
	global_load_lds_dwordx4 v[178:179], off
	v_lshl_add_u64 v[178:179], v[168:169], 0, s[90:91]
	s_mov_b32 m0, s25
	s_nop 0
	global_load_lds_dwordx4 v[178:179], off
	s_waitcnt vmcnt(8)
	s_waitcnt lgkmcnt(0)
	s_barrier
	s_setprio 1
	s_waitcnt lgkmcnt(0)
	v_mfma_scale_f32_16x16x128_f8f6f4 v[156:159], v[0:7], v[194:201], v[156:159], v240, v240 op_sel_hi:[0,0,0]
	v_mfma_scale_f32_16x16x128_f8f6f4 v[148:151], v[8:15], v[194:201], v[148:151], v240, v240 op_sel_hi:[0,0,0]
	v_mfma_scale_f32_16x16x128_f8f6f4 v[140:143], v[0:7], v[202:209], v[140:143], v240, v240 op_sel_hi:[0,0,0]
	v_mfma_scale_f32_16x16x128_f8f6f4 v[132:135], v[8:15], v[202:209], v[132:135], v240, v240 op_sel_hi:[0,0,0]
	v_mfma_scale_f32_16x16x128_f8f6f4 v[124:127], v[0:7], v[210:217], v[124:127], v240, v240 op_sel_hi:[0,0,0]
	v_mfma_scale_f32_16x16x128_f8f6f4 v[116:119], v[8:15], v[210:217], v[116:119], v240, v240 op_sel_hi:[0,0,0]
	v_mfma_scale_f32_16x16x128_f8f6f4 v[108:111], v[0:7], v[218:225], v[108:111], v240, v240 op_sel_hi:[0,0,0]
	v_mfma_scale_f32_16x16x128_f8f6f4 v[100:103], v[8:15], v[218:225], v[100:103], v240, v240 op_sel_hi:[0,0,0]
	s_setprio 0
	s_setprio 1
	v_mfma_scale_f32_16x16x128_f8f6f4 v[152:155], v[16:23], v[194:201], v[152:155], v240, v240 op_sel_hi:[0,0,0]
	v_mfma_scale_f32_16x16x128_f8f6f4 v[144:147], v[24:31], v[194:201], v[144:147], v240, v240 op_sel_hi:[0,0,0]
	v_mfma_scale_f32_16x16x128_f8f6f4 v[136:139], v[16:23], v[202:209], v[136:139], v240, v240 op_sel_hi:[0,0,0]
	v_mfma_scale_f32_16x16x128_f8f6f4 v[128:131], v[24:31], v[202:209], v[128:131], v240, v240 op_sel_hi:[0,0,0]
	v_mfma_scale_f32_16x16x128_f8f6f4 v[120:123], v[16:23], v[210:217], v[120:123], v240, v240 op_sel_hi:[0,0,0]
	v_mfma_scale_f32_16x16x128_f8f6f4 v[112:115], v[24:31], v[210:217], v[112:115], v240, v240 op_sel_hi:[0,0,0]
	v_mfma_scale_f32_16x16x128_f8f6f4 v[104:107], v[16:23], v[218:225], v[104:107], v240, v240 op_sel_hi:[0,0,0]
	v_mfma_scale_f32_16x16x128_f8f6f4 v[96:99], v[24:31], v[218:225], v[96:99], v240, v240 op_sel_hi:[0,0,0]
	s_setprio 0
	s_barrier
	s_add_i32 s14, s14, s6
	v_lshl_add_u64 v[178:179], v[166:167], 0, s[56:57]
	s_mov_b32 m0, s14
	ds_read_b128 v[194:197], v176 offset:49152
	ds_read_b128 v[198:201], v176 offset:50176
	ds_read_b128 v[202:205], v176 offset:51200
	ds_read_b128 v[206:209], v176 offset:52224
	ds_read_b128 v[210:213], v176 offset:53248
	ds_read_b128 v[214:217], v176 offset:54272
	ds_read_b128 v[218:221], v176 offset:55296
	ds_read_b128 v[222:225], v176 offset:56320
	global_load_lds_dwordx4 v[178:179], off
	v_lshl_add_u64 v[178:179], v[166:167], 0, s[58:59]
	s_add_i32 m0, s14, 0x2000
	s_add_i32 s14, s15, s6
	global_load_lds_dwordx4 v[178:179], off
	v_lshl_add_u64 v[178:179], v[166:167], 0, s[96:97]
	s_mov_b32 m0, s14
	v_lshl_add_u64 v[166:167], v[166:167], 0, s[4:5]
	global_load_lds_dwordx4 v[178:179], off
	s_add_i32 m0, s14, 0x2000
	s_nop 0
	global_load_lds_dwordx4 v[166:167], off
	v_lshl_add_u64 v[166:167], v[168:169], 0, s[56:57]
	s_mov_b32 m0, s26
	s_nop 0
	global_load_lds_dwordx4 v[166:167], off
	v_lshl_add_u64 v[166:167], v[168:169], 0, s[58:59]
	s_mov_b32 m0, s27
	s_nop 0
	global_load_lds_dwordx4 v[166:167], off
	s_waitcnt vmcnt(8)
	s_waitcnt lgkmcnt(0)
	s_barrier
	s_setprio 1
	s_waitcnt lgkmcnt(0)
	v_mfma_scale_f32_16x16x128_f8f6f4 v[92:95], v[0:7], v[194:201], v[92:95], v240, v240 op_sel_hi:[0,0,0]
	v_mfma_scale_f32_16x16x128_f8f6f4 v[84:87], v[8:15], v[194:201], v[84:87], v240, v240 op_sel_hi:[0,0,0]
	v_mfma_scale_f32_16x16x128_f8f6f4 v[76:79], v[0:7], v[202:209], v[76:79], v240, v240 op_sel_hi:[0,0,0]
	v_mfma_scale_f32_16x16x128_f8f6f4 v[68:71], v[8:15], v[202:209], v[68:71], v240, v240 op_sel_hi:[0,0,0]
	v_mfma_scale_f32_16x16x128_f8f6f4 v[60:63], v[0:7], v[210:217], v[60:63], v240, v240 op_sel_hi:[0,0,0]
	v_mfma_scale_f32_16x16x128_f8f6f4 v[52:55], v[8:15], v[210:217], v[52:55], v240, v240 op_sel_hi:[0,0,0]
	v_mfma_scale_f32_16x16x128_f8f6f4 v[44:47], v[0:7], v[218:225], v[44:47], v240, v240 op_sel_hi:[0,0,0]
	v_mfma_scale_f32_16x16x128_f8f6f4 v[36:39], v[8:15], v[218:225], v[36:39], v240, v240 op_sel_hi:[0,0,0]
	s_setprio 0
	s_setprio 1
	v_mfma_scale_f32_16x16x128_f8f6f4 v[88:91], v[16:23], v[194:201], v[88:91], v240, v240 op_sel_hi:[0,0,0]
	v_mfma_scale_f32_16x16x128_f8f6f4 v[80:83], v[24:31], v[194:201], v[80:83], v240, v240 op_sel_hi:[0,0,0]
	v_mfma_scale_f32_16x16x128_f8f6f4 v[72:75], v[16:23], v[202:209], v[72:75], v240, v240 op_sel_hi:[0,0,0]
	v_mfma_scale_f32_16x16x128_f8f6f4 v[64:67], v[24:31], v[202:209], v[64:67], v240, v240 op_sel_hi:[0,0,0]
	v_mfma_scale_f32_16x16x128_f8f6f4 v[56:59], v[16:23], v[210:217], v[56:59], v240, v240 op_sel_hi:[0,0,0]
	v_mfma_scale_f32_16x16x128_f8f6f4 v[48:51], v[24:31], v[210:217], v[48:51], v240, v240 op_sel_hi:[0,0,0]
	v_mfma_scale_f32_16x16x128_f8f6f4 v[40:43], v[16:23], v[218:225], v[40:43], v240, v240 op_sel_hi:[0,0,0]
	v_mfma_scale_f32_16x16x128_f8f6f4 v[32:35], v[24:31], v[218:225], v[32:35], v240, v240 op_sel_hi:[0,0,0]
	s_setprio 0
	s_barrier
	s_add_i32 s51, s51, 2
	s_add_u32 s46, s46, 0x100
	s_addc_u32 s47, s47, 0
	s_add_u32 s49, s49, 0x100
	s_addc_u32 s50, s50, 0
	s_cmp_gt_u32 s51, 5
